# first K-loop iteration of every GEMM unit peeled with C=0 first-touch MFMAs; accumulator zeroing removed
# speedup vs baseline: 1.0128x; 1.0041x over previous
; #define PG8_STAGE(bufoff, gbase, voff) do { _Pragma("unroll") for (int _i = 0; _i < 2; ++_i) \
;         __builtin_amdgcn_global_load_lds((const unsigned*)((const char*)(gbase) + (voff)[_i]), (PG8_LAS unsigned*)(lds + (bufoff) + ldsw + _i * 8192), 16, 0, 0); } while (0)
; #define PG8_LDA(dst, b, h) do { _Pragma("unroll") for (int m = 0; m < 4; ++m) _Pragma("unroll") for (int k = 0; k < 2; ++k) dst[m][k] = *(const PG8_LAS bf16x8*)(lds + PG8_SA(b, h) + aoff + m * 2048 + k * 1024); } while (0)
; #define PG8_LDB(dst, b, h) do { _Pragma("unroll") for (int n = 0; n < 2; ++n) _Pragma("unroll") for (int k = 0; k < 2; ++k) dst[n][k] = *(const PG8_LAS bf16x8*)(lds + PG8_SB(b, h) + boff + n * 2048 + k * 1024); } while (0)
; #define PG8_WAIT_V(n) asm volatile("s_waitcnt vmcnt(" #n ")" ::: "memory")
; #define PG8_WAIT_L(n) asm volatile("s_waitcnt lgkmcnt(" #n ")" ::: "memory")
; #define PG8_BAR __builtin_amdgcn_s_barrier()
; #define PG8_SCHED __builtin_amdgcn_sched_barrier(0)
; template <class Epi, class Sched, bool ALIGN_EPI = false, bool SP2 = false>
; __device__ __forceinline__ void gemm_phase(PG8_LAS unsigned char* lds, const Gemm g, const Sched& S, const Epi& E) {
;     ...
;         const bool has_next = S.next(ui + 1, nxt);
;         const char* nA = has_next ? (const char*)g.A + (size_t)nxt.pm * tstep : cA; const char* nB = has_next ? (const char*)g.Bt + (size_t)nxt.pn * tstep : cB;
;         for (int t = 0; t < nt; t += 2) {
;             const bool last = (t == nt - 2);
;             const char* a1 = cA + (size_t)(t + 1) * kstep;
;             const char* a2 = last ? nA : cA + (size_t)(t + 2) * kstep; const char* b2 = last ? nB : cB + (size_t)(t + 2) * kstep;
;             const char* a3 = a2 + kstep; const char* b3 = b2 + kstep;
;             if (last && has_next) S.a_ready(nxt);
;             if constexpr (SP2) {
;             PG8_LDB(B0, 0, 0); PG8_LDB(B1, 0, 1); PG8_SCHED; PG8_LDA(At, 0, 0); PG8_STAGE(PG8_SA(1, 1), a1 + hstep, voffA);
;             PG8_WAIT_V(8); PG8_WAIT_L(0); PG8_BAR; PG8_MMA(0, 0, At, B0); PG8_MMA(0, 1, At, B1); PG8_BAR; PG8_SCHED;
;             PG8_LDA(At, 0, 1); PG8_STAGE(PG8_SB(0, 0), b2, voffB); PG8_STAGE(PG8_SB(0, 1), b2 + hstep, voffB); PG8_STAGE(PG8_SA(0, 0), a2, voffA);
;             PG8_WAIT_V(8); PG8_WAIT_L(0); PG8_BAR; PG8_MMA(1, 0, At, B0); PG8_MMA(1, 1, At, B1); PG8_BAR; PG8_SCHED;
.LBB0_133:
	s_ashr_i32 s27, s26, 31
	s_lshl_b64 s[28:29], s[26:27], 19
	s_add_u32 s28, s76, s28
	s_addc_u32 s29, s77, s29
	s_and_b64 s[30:31], s[4:5], exec
	s_cselect_b32 s1, s29, s35
	s_cselect_b32 s7, s28, s34
	s_ashr_i32 s15, s14, 31
	s_lshl_b64 s[30:31], s[14:15], 19
	s_add_u32 s30, s24, s30
	s_addc_u32 s31, s25, s31
	s_and_b64 s[38:39], s[4:5], exec
	s_cselect_b32 s15, s31, s37
	s_cselect_b32 s27, s30, s36
	s_add_u32 s34, s34, 0x40080
	s_addc_u32 s35, s35, 0
	s_add_u32 s87, s36, 0x100
	s_addc_u32 s88, s37, 0
	s_mov_b32 s89, -2
	ds_read_b128 v[136:139], v151
	ds_read_b128 v[168:171], v151 offset:1024
	ds_read_b128 v[176:179], v151 offset:2048
	ds_read_b128 v[180:183], v151 offset:3072
	ds_read_b128 v[184:187], v164
	ds_read_b128 v[188:191], v164 offset:1024
	ds_read_b128 v[192:195], v164 offset:2048
	ds_read_b128 v[196:199], v164 offset:3072
	s_add_u32 s36, s34, 0xfffc0080
	s_addc_u32 s37, s35, -1
	s_cmp_eq_u32 s89, 12
	s_cselect_b32 s39, s1, s37
	s_cselect_b32 s38, s7, s36
	s_cselect_b32 s37, s15, s88
	s_cselect_b32 s36, s27, s87
	v_lshl_add_u64 v[228:229], s[34:35], 0, v[128:129]
	s_add_i32 m0, s33, 0xc000
	ds_read_b128 v[200:203], v165
	ds_read_b128 v[204:207], v165 offset:1024
	ds_read_b128 v[208:211], v165 offset:2048
	ds_read_b128 v[212:215], v165 offset:3072
	ds_read_b128 v[216:219], v165 offset:4096
	ds_read_b128 v[220:223], v165 offset:5120
	ds_read_b128 v[224:227], v165 offset:6144
	ds_read_b128 v[240:243], v165 offset:7168
	global_load_lds_dwordx4 v[228:229], off
	v_lshl_add_u64 v[228:229], s[34:35], 0, v[130:131]
	s_add_i32 m0, s33, 0xe000
	s_nop 0
	global_load_lds_dwordx4 v[228:229], off
	s_waitcnt vmcnt(8)
	s_waitcnt lgkmcnt(0)
	s_setprio 1
	s_barrier
	v_mfma_f32_16x16x32_bf16 v[124:127], v[136:139], v[200:203], 0
	v_mfma_f32_16x16x32_bf16 v[116:119], v[176:179], v[200:203], 0
	v_mfma_f32_16x16x32_bf16 v[108:111], v[136:139], v[208:211], 0
	v_mfma_f32_16x16x32_bf16 v[100:103], v[176:179], v[208:211], 0
	v_mfma_f32_16x16x32_bf16 v[92:95], v[136:139], v[216:219], 0
	v_mfma_f32_16x16x32_bf16 v[84:87], v[176:179], v[216:219], 0
	v_mfma_f32_16x16x32_bf16 v[76:79], v[136:139], v[224:227], 0
	v_mfma_f32_16x16x32_bf16 v[68:71], v[176:179], v[224:227], 0
	v_mfma_f32_16x16x32_bf16 v[124:127], v[168:171], v[204:207], v[124:127]
	v_mfma_f32_16x16x32_bf16 v[116:119], v[180:183], v[204:207], v[116:119]
	v_mfma_f32_16x16x32_bf16 v[108:111], v[168:171], v[212:215], v[108:111]
	v_mfma_f32_16x16x32_bf16 v[100:103], v[180:183], v[212:215], v[100:103]
	v_mfma_f32_16x16x32_bf16 v[92:95], v[168:171], v[220:223], v[92:95]
	v_mfma_f32_16x16x32_bf16 v[84:87], v[180:183], v[220:223], v[84:87]
	v_mfma_f32_16x16x32_bf16 v[76:79], v[168:171], v[240:243], v[76:79]
	v_mfma_f32_16x16x32_bf16 v[68:71], v[180:183], v[240:243], v[68:71]
	s_setprio 0
	s_setprio 1
	v_mfma_f32_16x16x32_bf16 v[120:123], v[184:187], v[200:203], 0
	v_mfma_f32_16x16x32_bf16 v[112:115], v[192:195], v[200:203], 0
	v_mfma_f32_16x16x32_bf16 v[104:107], v[184:187], v[208:211], 0
	v_mfma_f32_16x16x32_bf16 v[96:99], v[192:195], v[208:211], 0
	v_mfma_f32_16x16x32_bf16 v[88:91], v[184:187], v[216:219], 0
	v_mfma_f32_16x16x32_bf16 v[80:83], v[192:195], v[216:219], 0
	v_mfma_f32_16x16x32_bf16 v[72:75], v[184:187], v[224:227], 0
	v_mfma_f32_16x16x32_bf16 v[64:67], v[192:195], v[224:227], 0
	v_mfma_f32_16x16x32_bf16 v[120:123], v[188:191], v[204:207], v[120:123]
	v_mfma_f32_16x16x32_bf16 v[112:115], v[196:199], v[204:207], v[112:115]
	v_mfma_f32_16x16x32_bf16 v[104:107], v[188:191], v[212:215], v[104:107]
	v_mfma_f32_16x16x32_bf16 v[96:99], v[196:199], v[212:215], v[96:99]
	v_mfma_f32_16x16x32_bf16 v[88:91], v[188:191], v[220:223], v[88:91]
	v_mfma_f32_16x16x32_bf16 v[80:83], v[196:199], v[220:223], v[80:83]
	v_mfma_f32_16x16x32_bf16 v[72:75], v[188:191], v[240:243], v[72:75]
	v_mfma_f32_16x16x32_bf16 v[64:67], v[196:199], v[240:243], v[64:67]
	s_barrier
	s_setprio 0
	s_add_i32 s90, s82, s3
	v_lshl_add_u64 v[228:229], s[36:37], 0, v[158:159]
	s_mov_b32 m0, s90
	ds_read_b128 v[200:203], v165 offset:16384
	ds_read_b128 v[204:207], v165 offset:17408
	ds_read_b128 v[208:211], v165 offset:18432
	ds_read_b128 v[212:215], v165 offset:19456
	ds_read_b128 v[216:219], v165 offset:20480
	ds_read_b128 v[220:223], v165 offset:21504
	ds_read_b128 v[224:227], v165 offset:22528
	ds_read_b128 v[240:243], v165 offset:23552
	global_load_lds_dwordx4 v[228:229], off
	s_add_i32 m0, s90, 0x2000
	s_add_u32 s90, s36, 0x40000
	v_lshl_add_u64 v[244:245], s[36:37], 0, v[162:163]
	s_addc_u32 s91, s37, 0
	s_add_i32 s93, s83, s3
	global_load_lds_dwordx4 v[244:245], off
	v_lshl_add_u64 v[248:249], s[90:91], 0, v[158:159]
	s_mov_b32 m0, s93
	v_lshl_add_u64 v[250:251], s[38:39], 0, v[160:161]
	global_load_lds_dwordx4 v[248:249], off
	v_lshl_add_u64 v[248:249], s[90:91], 0, v[162:163]
	s_add_i32 m0, s93, 0x2000
	s_nop 0
	global_load_lds_dwordx4 v[248:249], off
	v_lshl_add_u64 v[248:249], s[38:39], 0, v[156:157]
	s_mov_b32 m0, s33
	s_nop 0
	global_load_lds_dwordx4 v[248:249], off
	s_mov_b32 m0, s40
	s_nop 0
	global_load_lds_dwordx4 v[250:251], off
	s_waitcnt vmcnt(8)
	s_waitcnt lgkmcnt(0)
	s_setprio 1
	s_barrier
; #define PG8_STAGE(bufoff, gbase, voff) do { _Pragma("unroll") for (int _i = 0; _i < 2; ++_i) \
;         __builtin_amdgcn_global_load_lds((const unsigned*)((const char*)(gbase) + (voff)[_i]), (PG8_LAS unsigned*)(lds + (bufoff) + ldsw + _i * 8192), 16, 0, 0); } while (0)
; #define PG8_LDA(dst, b, h) do { _Pragma("unroll") for (int m = 0; m < 4; ++m) _Pragma("unroll") for (int k = 0; k < 2; ++k) dst[m][k] = *(const PG8_LAS bf16x8*)(lds + PG8_SA(b, h) + aoff + m * 2048 + k * 1024); } while (0)
; #define PG8_LDB(dst, b, h) do { _Pragma("unroll") for (int n = 0; n < 2; ++n) _Pragma("unroll") for (int k = 0; k < 2; ++k) dst[n][k] = *(const PG8_LAS bf16x8*)(lds + PG8_SB(b, h) + boff + n * 2048 + k * 1024); } while (0)
; #define PG8_MMA(ai, bj, At, Bt) do { __builtin_amdgcn_s_setprio(1); _Pragma("unroll") for (int m = 0; m < 4; ++m) _Pragma("unroll") for (int n = 0; n < 2; ++n) _Pragma("unroll") for (int k = 0; k < 2; ++k) \
;         acc[ai][bj][m][n] = __builtin_amdgcn_mfma_f32_16x16x32_bf16(Bt[n][k], At[m][k], acc[ai][bj][m][n], 0, 0, 0); __builtin_amdgcn_s_setprio(0); } while (0)
; #define PG8_WAIT_V(n) asm volatile("s_waitcnt vmcnt(" #n ")" ::: "memory")
; #define PG8_WAIT_L(n) asm volatile("s_waitcnt lgkmcnt(" #n ")" ::: "memory")
; #define PG8_BAR __builtin_amdgcn_s_barrier()
; #define PG8_SCHED __builtin_amdgcn_sched_barrier(0)
; template <class Epi, class Sched, bool ALIGN_EPI = false, bool SP2 = false>
; __device__ __forceinline__ void gemm_phase(PG8_LAS unsigned char* lds, const Gemm g, const Sched& S, const Epi& E) {
;     ...
;             PG8_WAIT_V(8); PG8_WAIT_L(0); PG8_BAR; PG8_MMA(1, 0, At, B0); PG8_MMA(1, 1, At, B1); PG8_BAR; PG8_SCHED;
;             PG8_LDB(B0, 1, 0); PG8_LDB(B1, 1, 1); PG8_SCHED; PG8_LDA(At, 1, 0); PG8_STAGE(PG8_SA(0, 1), a2 + hstep, voffA);
;             PG8_WAIT_V(8); PG8_WAIT_L(0); PG8_BAR; PG8_MMA(0, 0, At, B0); PG8_MMA(0, 1, At, B1); PG8_BAR; PG8_SCHED;
	v_mfma_f32_16x16x32_bf16 v[60:63], v[136:139], v[200:203], 0
	v_mfma_f32_16x16x32_bf16 v[52:55], v[176:179], v[200:203], 0
	v_mfma_f32_16x16x32_bf16 v[44:47], v[136:139], v[208:211], 0
	v_mfma_f32_16x16x32_bf16 v[36:39], v[176:179], v[208:211], 0
	v_mfma_f32_16x16x32_bf16 v[28:31], v[136:139], v[216:219], 0
	v_mfma_f32_16x16x32_bf16 v[20:23], v[176:179], v[216:219], 0
	v_mfma_f32_16x16x32_bf16 v[12:15], v[136:139], v[224:227], 0
	v_mfma_f32_16x16x32_bf16 v[4:7], v[176:179], v[224:227], 0
	v_mfma_f32_16x16x32_bf16 v[60:63], v[168:171], v[204:207], v[60:63]
	v_mfma_f32_16x16x32_bf16 v[52:55], v[180:183], v[204:207], v[52:55]
	v_mfma_f32_16x16x32_bf16 v[44:47], v[168:171], v[212:215], v[44:47]
	v_mfma_f32_16x16x32_bf16 v[36:39], v[180:183], v[212:215], v[36:39]
	v_mfma_f32_16x16x32_bf16 v[28:31], v[168:171], v[220:223], v[28:31]
	v_mfma_f32_16x16x32_bf16 v[20:23], v[180:183], v[220:223], v[20:23]
	v_mfma_f32_16x16x32_bf16 v[12:15], v[168:171], v[240:243], v[12:15]
	v_mfma_f32_16x16x32_bf16 v[4:7], v[180:183], v[240:243], v[4:7]
	s_setprio 0
	s_setprio 1
	v_mfma_f32_16x16x32_bf16 v[56:59], v[184:187], v[200:203], 0
	v_mfma_f32_16x16x32_bf16 v[48:51], v[192:195], v[200:203], 0
	v_mfma_f32_16x16x32_bf16 v[40:43], v[184:187], v[208:211], 0
	v_mfma_f32_16x16x32_bf16 v[32:35], v[192:195], v[208:211], 0
	v_mfma_f32_16x16x32_bf16 v[24:27], v[184:187], v[216:219], 0
	v_mfma_f32_16x16x32_bf16 v[16:19], v[192:195], v[216:219], 0
	v_mfma_f32_16x16x32_bf16 v[8:11], v[184:187], v[224:227], 0
	v_mfma_f32_16x16x32_bf16 v[0:3], v[192:195], v[224:227], 0
	v_mfma_f32_16x16x32_bf16 v[56:59], v[188:191], v[204:207], v[56:59]
	v_mfma_f32_16x16x32_bf16 v[48:51], v[196:199], v[204:207], v[48:51]
	v_mfma_f32_16x16x32_bf16 v[40:43], v[188:191], v[212:215], v[40:43]
	v_mfma_f32_16x16x32_bf16 v[32:35], v[196:199], v[212:215], v[32:35]
	v_mfma_f32_16x16x32_bf16 v[24:27], v[188:191], v[220:223], v[24:27]
	v_mfma_f32_16x16x32_bf16 v[16:19], v[196:199], v[220:223], v[16:19]
	v_mfma_f32_16x16x32_bf16 v[8:11], v[188:191], v[240:243], v[8:11]
	v_mfma_f32_16x16x32_bf16 v[0:3], v[196:199], v[240:243], v[0:3]
	s_barrier
	s_setprio 0
	s_add_i32 s90, 0, 0x18000
	v_add_u32_e32 v172, s90, v148
	s_add_i32 s91, 0, 0x1c000
	ds_read_b128 v[136:139], v172
	ds_read_b128 v[168:171], v172 offset:1024
	ds_read_b128 v[176:179], v172 offset:2048
	ds_read_b128 v[180:183], v172 offset:3072
	v_add_u32_e32 v172, s91, v148
	ds_read_b128 v[184:187], v172
	ds_read_b128 v[188:191], v172 offset:1024
	ds_read_b128 v[192:195], v172 offset:2048
	ds_read_b128 v[196:199], v172 offset:3072
	s_add_u32 s38, s38, 0x40000
	s_addc_u32 s39, s39, 0
	s_mov_b32 m0, s41
	v_lshl_add_u64 v[252:253], s[38:39], 0, v[156:157]
	ds_read_b128 v[200:203], v165 offset:32768
	ds_read_b128 v[204:207], v165 offset:33792
	ds_read_b128 v[208:211], v165 offset:34816
	ds_read_b128 v[212:215], v165 offset:35840
	ds_read_b128 v[216:219], v165 offset:36864
	ds_read_b128 v[220:223], v165 offset:37888
	ds_read_b128 v[224:227], v165 offset:38912
	ds_read_b128 v[240:243], v165 offset:39936
	global_load_lds_dwordx4 v[252:253], off
	v_lshl_add_u64 v[252:253], s[38:39], 0, v[160:161]
	s_mov_b32 m0, s42
	s_nop 0
	global_load_lds_dwordx4 v[252:253], off
	s_waitcnt vmcnt(8)
	s_waitcnt lgkmcnt(0)
	s_setprio 1
	s_barrier
	v_mfma_f32_16x16x32_bf16 v[124:127], v[136:139], v[200:203], v[124:127]
	v_mfma_f32_16x16x32_bf16 v[116:119], v[176:179], v[200:203], v[116:119]
	v_mfma_f32_16x16x32_bf16 v[108:111], v[136:139], v[208:211], v[108:111]
	v_mfma_f32_16x16x32_bf16 v[100:103], v[176:179], v[208:211], v[100:103]
	v_mfma_f32_16x16x32_bf16 v[92:95], v[136:139], v[216:219], v[92:95]
	v_mfma_f32_16x16x32_bf16 v[84:87], v[176:179], v[216:219], v[84:87]
	v_mfma_f32_16x16x32_bf16 v[76:79], v[136:139], v[224:227], v[76:79]
	v_mfma_f32_16x16x32_bf16 v[68:71], v[176:179], v[224:227], v[68:71]
	v_mfma_f32_16x16x32_bf16 v[124:127], v[168:171], v[204:207], v[124:127]
	v_mfma_f32_16x16x32_bf16 v[116:119], v[180:183], v[204:207], v[116:119]
	v_mfma_f32_16x16x32_bf16 v[108:111], v[168:171], v[212:215], v[108:111]
	v_mfma_f32_16x16x32_bf16 v[100:103], v[180:183], v[212:215], v[100:103]
	v_mfma_f32_16x16x32_bf16 v[92:95], v[168:171], v[220:223], v[92:95]
	v_mfma_f32_16x16x32_bf16 v[84:87], v[180:183], v[220:223], v[84:87]
	v_mfma_f32_16x16x32_bf16 v[76:79], v[168:171], v[240:243], v[76:79]
	v_mfma_f32_16x16x32_bf16 v[68:71], v[180:183], v[240:243], v[68:71]
	s_setprio 0
	s_setprio 1
	v_mfma_f32_16x16x32_bf16 v[120:123], v[184:187], v[200:203], v[120:123]
	v_mfma_f32_16x16x32_bf16 v[112:115], v[192:195], v[200:203], v[112:115]
	v_mfma_f32_16x16x32_bf16 v[104:107], v[184:187], v[208:211], v[104:107]
	v_mfma_f32_16x16x32_bf16 v[96:99], v[192:195], v[208:211], v[96:99]
	v_mfma_f32_16x16x32_bf16 v[88:91], v[184:187], v[216:219], v[88:91]
	v_mfma_f32_16x16x32_bf16 v[80:83], v[192:195], v[216:219], v[80:83]
	v_mfma_f32_16x16x32_bf16 v[72:75], v[184:187], v[224:227], v[72:75]
	v_mfma_f32_16x16x32_bf16 v[64:67], v[192:195], v[224:227], v[64:67]
	v_mfma_f32_16x16x32_bf16 v[120:123], v[188:191], v[204:207], v[120:123]
	v_mfma_f32_16x16x32_bf16 v[112:115], v[196:199], v[204:207], v[112:115]
	v_mfma_f32_16x16x32_bf16 v[104:107], v[188:191], v[212:215], v[104:107]
	v_mfma_f32_16x16x32_bf16 v[96:99], v[196:199], v[212:215], v[96:99]
	v_mfma_f32_16x16x32_bf16 v[88:91], v[188:191], v[220:223], v[88:91]
	v_mfma_f32_16x16x32_bf16 v[80:83], v[196:199], v[220:223], v[80:83]
	v_mfma_f32_16x16x32_bf16 v[72:75], v[188:191], v[240:243], v[72:75]
	v_mfma_f32_16x16x32_bf16 v[64:67], v[196:199], v[240:243], v[64:67]
	s_barrier
; #define PG8_STAGE(bufoff, gbase, voff) do { _Pragma("unroll") for (int _i = 0; _i < 2; ++_i) \
;         __builtin_amdgcn_global_load_lds((const unsigned*)((const char*)(gbase) + (voff)[_i]), (PG8_LAS unsigned*)(lds + (bufoff) + ldsw + _i * 8192), 16, 0, 0); } while (0)
; #define PG8_LDA(dst, b, h) do { _Pragma("unroll") for (int m = 0; m < 4; ++m) _Pragma("unroll") for (int k = 0; k < 2; ++k) dst[m][k] = *(const PG8_LAS bf16x8*)(lds + PG8_SA(b, h) + aoff + m * 2048 + k * 1024); } while (0)
; #define PG8_MMA(ai, bj, At, Bt) do { __builtin_amdgcn_s_setprio(1); _Pragma("unroll") for (int m = 0; m < 4; ++m) _Pragma("unroll") for (int n = 0; n < 2; ++n) _Pragma("unroll") for (int k = 0; k < 2; ++k) \
;         acc[ai][bj][m][n] = __builtin_amdgcn_mfma_f32_16x16x32_bf16(Bt[n][k], At[m][k], acc[ai][bj][m][n], 0, 0, 0); __builtin_amdgcn_s_setprio(0); } while (0)
; #define PG8_WAIT_V(n) asm volatile("s_waitcnt vmcnt(" #n ")" ::: "memory")
; #define PG8_WAIT_L(n) asm volatile("s_waitcnt lgkmcnt(" #n ")" ::: "memory")
; #define PG8_BAR __builtin_amdgcn_s_barrier()
; #define PG8_SCHED __builtin_amdgcn_sched_barrier(0)
; template <class Epi, class Sched, bool ALIGN_EPI = false, bool SP2 = false>
; __device__ __forceinline__ void gemm_phase(PG8_LAS unsigned char* lds, const Gemm g, const Sched& S, const Epi& E) {
;     ...
;         for (int t = 0; t < nt; t += 2) {
;     ...
;             PG8_LDA(At, 1, 1); PG8_STAGE(PG8_SB(1, 0), b3, voffB); PG8_STAGE(PG8_SB(1, 1), b3 + hstep, voffB); PG8_STAGE(PG8_SA(1, 0), a3, voffA);
;             PG8_WAIT_V(8); PG8_WAIT_L(0); PG8_BAR; PG8_MMA(1, 0, At, B0); PG8_MMA(1, 1, At, B1); PG8_BAR; PG8_SCHED;
	s_setprio 0
	s_add_i32 s38, s90, s3
	v_lshl_add_u64 v[228:229], v[228:229], 0, s[10:11]
	s_mov_b32 m0, s38
	ds_read_b128 v[200:203], v165 offset:49152
	ds_read_b128 v[204:207], v165 offset:50176
	ds_read_b128 v[208:211], v165 offset:51200
	ds_read_b128 v[212:215], v165 offset:52224
	ds_read_b128 v[216:219], v165 offset:53248
	ds_read_b128 v[220:223], v165 offset:54272
	ds_read_b128 v[224:227], v165 offset:55296
	ds_read_b128 v[240:243], v165 offset:56320
	global_load_lds_dwordx4 v[228:229], off
	s_add_i32 m0, s38, 0x2000
	s_add_u32 s36, s36, 0x40080
	v_lshl_add_u64 v[228:229], v[244:245], 0, s[10:11]
	s_addc_u32 s37, s37, 0
	s_add_i32 s38, s91, s3
	global_load_lds_dwordx4 v[228:229], off
	v_lshl_add_u64 v[228:229], s[36:37], 0, v[158:159]
	s_mov_b32 m0, s38
	s_nop 0
	global_load_lds_dwordx4 v[228:229], off
	v_lshl_add_u64 v[228:229], s[36:37], 0, v[162:163]
	s_add_i32 m0, s38, 0x2000
	s_nop 0
	global_load_lds_dwordx4 v[228:229], off
	v_lshl_add_u64 v[228:229], v[248:249], 0, s[10:11]
	s_mov_b32 m0, s44
	s_nop 0
	global_load_lds_dwordx4 v[228:229], off
	v_lshl_add_u64 v[228:229], v[250:251], 0, s[10:11]
	s_mov_b32 m0, s45
	s_nop 0
	global_load_lds_dwordx4 v[228:229], off
	s_waitcnt vmcnt(8)
	s_waitcnt lgkmcnt(0)
	s_setprio 1
	s_barrier
	v_mfma_f32_16x16x32_bf16 v[60:63], v[136:139], v[200:203], v[60:63]
	v_mfma_f32_16x16x32_bf16 v[52:55], v[176:179], v[200:203], v[52:55]
	v_mfma_f32_16x16x32_bf16 v[44:47], v[136:139], v[208:211], v[44:47]
	v_mfma_f32_16x16x32_bf16 v[36:39], v[176:179], v[208:211], v[36:39]
	v_mfma_f32_16x16x32_bf16 v[28:31], v[136:139], v[216:219], v[28:31]
	v_mfma_f32_16x16x32_bf16 v[20:23], v[176:179], v[216:219], v[20:23]
	v_mfma_f32_16x16x32_bf16 v[12:15], v[136:139], v[224:227], v[12:15]
	v_mfma_f32_16x16x32_bf16 v[4:7], v[176:179], v[224:227], v[4:7]
	v_mfma_f32_16x16x32_bf16 v[60:63], v[168:171], v[204:207], v[60:63]
	v_mfma_f32_16x16x32_bf16 v[52:55], v[180:183], v[204:207], v[52:55]
	v_mfma_f32_16x16x32_bf16 v[44:47], v[168:171], v[212:215], v[44:47]
	v_mfma_f32_16x16x32_bf16 v[36:39], v[180:183], v[212:215], v[36:39]
	v_mfma_f32_16x16x32_bf16 v[28:31], v[168:171], v[220:223], v[28:31]
	v_mfma_f32_16x16x32_bf16 v[20:23], v[180:183], v[220:223], v[20:23]
	v_mfma_f32_16x16x32_bf16 v[12:15], v[168:171], v[240:243], v[12:15]
	v_mfma_f32_16x16x32_bf16 v[4:7], v[180:183], v[240:243], v[4:7]
	s_setprio 0
	s_setprio 1
	v_mfma_f32_16x16x32_bf16 v[56:59], v[184:187], v[200:203], v[56:59]
	v_mfma_f32_16x16x32_bf16 v[48:51], v[192:195], v[200:203], v[48:51]
	v_mfma_f32_16x16x32_bf16 v[40:43], v[184:187], v[208:211], v[40:43]
	v_mfma_f32_16x16x32_bf16 v[32:35], v[192:195], v[208:211], v[32:35]
	v_mfma_f32_16x16x32_bf16 v[24:27], v[184:187], v[216:219], v[24:27]
	v_mfma_f32_16x16x32_bf16 v[16:19], v[192:195], v[216:219], v[16:19]
	v_mfma_f32_16x16x32_bf16 v[8:11], v[184:187], v[224:227], v[8:11]
	v_mfma_f32_16x16x32_bf16 v[0:3], v[192:195], v[224:227], v[0:3]
	v_mfma_f32_16x16x32_bf16 v[56:59], v[188:191], v[204:207], v[56:59]
	v_mfma_f32_16x16x32_bf16 v[48:51], v[196:199], v[204:207], v[48:51]
	v_mfma_f32_16x16x32_bf16 v[40:43], v[188:191], v[212:215], v[40:43]
	v_mfma_f32_16x16x32_bf16 v[32:35], v[196:199], v[212:215], v[32:35]
	v_mfma_f32_16x16x32_bf16 v[24:27], v[188:191], v[220:223], v[24:27]
	v_mfma_f32_16x16x32_bf16 v[16:19], v[196:199], v[220:223], v[16:19]
	v_mfma_f32_16x16x32_bf16 v[8:11], v[188:191], v[240:243], v[8:11]
	v_mfma_f32_16x16x32_bf16 v[0:3], v[196:199], v[240:243], v[0:3]
	s_barrier
	s_setprio 0
	s_add_i32 s89, s89, 2
	s_add_u32 s34, s34, 0x100
	s_addc_u32 s35, s35, 0
	s_add_u32 s87, s87, 0x100
	s_addc_u32 s88, s88, 0
	s_cmp_gt_u32 s89, 13
	s_cbranch_scc1 .Lpeel_done_g0

; #define PG8_BAR __builtin_amdgcn_s_barrier()
; template <class Epi, class Sched, bool ALIGN_EPI = false, bool SP2 = false>
; __device__ __forceinline__ void gemm_phase(PG8_LAS unsigned char* lds, const Gemm g, const Sched& S, const Epi& E) {
;     ...
;         if constexpr (ALIGN_EPI) { if (wr == 0) PG8_BAR; }
;         if constexpr (!Epi::AFTER_DRAIN) { E(acc, cur, wr, wc, fr, fq); S.done(cur); }
.Lpeel_done_g0:
	s_and_b64 vcc, exec, s[12:13]
	s_cbranch_vccz .LBB0_137
	s_barrier

; #define PG8_STAGE(bufoff, gbase, voff) do { _Pragma("unroll") for (int _i = 0; _i < 2; ++_i) \
;         __builtin_amdgcn_global_load_lds((const unsigned*)((const char*)(gbase) + (voff)[_i]), (PG8_LAS unsigned*)(lds + (bufoff) + ldsw + _i * 8192), 16, 0, 0); } while (0)
; #define PG8_LDA(dst, b, h) do { _Pragma("unroll") for (int m = 0; m < 4; ++m) _Pragma("unroll") for (int k = 0; k < 2; ++k) dst[m][k] = *(const PG8_LAS bf16x8*)(lds + PG8_SA(b, h) + aoff + m * 2048 + k * 1024); } while (0)
; #define PG8_LDB(dst, b, h) do { _Pragma("unroll") for (int n = 0; n < 2; ++n) _Pragma("unroll") for (int k = 0; k < 2; ++k) dst[n][k] = *(const PG8_LAS bf16x8*)(lds + PG8_SB(b, h) + boff + n * 2048 + k * 1024); } while (0)
; #define PG8_WAIT_V(n) asm volatile("s_waitcnt vmcnt(" #n ")" ::: "memory")
; #define PG8_WAIT_L(n) asm volatile("s_waitcnt lgkmcnt(" #n ")" ::: "memory")
; #define PG8_BAR __builtin_amdgcn_s_barrier()
; #define PG8_SCHED __builtin_amdgcn_sched_barrier(0)
; template <class Epi, class Sched, bool ALIGN_EPI = false, bool SP2 = false>
; __device__ __forceinline__ void gemm_phase(PG8_LAS unsigned char* lds, const Gemm g, const Sched& S, const Epi& E) {
;     ...
;         const bool has_next = S.next(ui + 1, nxt);
;         const char* nA = has_next ? (const char*)g.A + (size_t)nxt.pm * tstep : cA; const char* nB = has_next ? (const char*)g.Bt + (size_t)nxt.pn * tstep : cB;
;         for (int t = 0; t < nt; t += 2) {
;             const bool last = (t == nt - 2);
;             const char* a1 = cA + (size_t)(t + 1) * kstep;
;             const char* a2 = last ? nA : cA + (size_t)(t + 2) * kstep; const char* b2 = last ? nB : cB + (size_t)(t + 2) * kstep;
;             const char* a3 = a2 + kstep; const char* b3 = b2 + kstep;
;             if (last && has_next) S.a_ready(nxt);
;             if constexpr (SP2) {
;             PG8_LDB(B0, 0, 0); PG8_LDB(B1, 0, 1); PG8_SCHED; PG8_LDA(At, 0, 0); PG8_STAGE(PG8_SA(1, 1), a1 + hstep, voffA);
;             PG8_WAIT_V(8); PG8_WAIT_L(0); PG8_BAR; PG8_MMA(0, 0, At, B0); PG8_MMA(0, 1, At, B1); PG8_BAR; PG8_SCHED;
;             PG8_LDA(At, 0, 1); PG8_STAGE(PG8_SB(0, 0), b2, voffB); PG8_STAGE(PG8_SB(0, 1), b2 + hstep, voffB); PG8_STAGE(PG8_SA(0, 0), a2, voffA);
;             PG8_WAIT_V(8); PG8_WAIT_L(0); PG8_BAR; PG8_MMA(1, 0, At, B0); PG8_MMA(1, 1, At, B1); PG8_BAR; PG8_SCHED;
.LBB0_371:
	s_add_u32 s20, s20, 0xb0080
	s_addc_u32 s21, s21, 0
	s_add_u32 s46, s24, 0x100
	s_addc_u32 s47, s25, 0
	s_mov_b32 s54, -2
	s_waitcnt lgkmcnt(0)
	ds_read_b128 v[128:131], v161
	ds_read_b128 v[132:135], v161 offset:1024
	ds_read_b128 v[136:139], v161 offset:2048
	ds_read_b128 v[140:143], v161 offset:3072
	ds_read_b128 v[144:147], v163
	ds_read_b128 v[148:151], v163 offset:1024
	ds_read_b128 v[184:187], v163 offset:2048
	ds_read_b128 v[188:191], v163 offset:3072
	s_add_u32 s24, s20, 0xfff50080
	s_addc_u32 s25, s21, -1
	s_cmp_eq_u32 s54, 40
	s_cselect_b32 s27, s1, s25
	s_cselect_b32 s26, s0, s24
	s_cselect_b32 s25, s19, s47
	s_cselect_b32 s24, s18, s46
	v_lshl_add_u64 v[200:201], s[20:21], 0, v[176:177]
	s_add_i32 m0, s29, 0xc000
	ds_read_b128 v[192:195], v202
	ds_read_b128 v[196:199], v202 offset:1024
	ds_read_b128 v[204:207], v202 offset:2048
	ds_read_b128 v[208:211], v202 offset:3072
	ds_read_b128 v[212:215], v202 offset:4096
	ds_read_b128 v[216:219], v202 offset:5120
	ds_read_b128 v[220:223], v202 offset:6144
	ds_read_b128 v[224:227], v202 offset:7168
	global_load_lds_dwordx4 v[200:201], off
	v_lshl_add_u64 v[200:201], s[20:21], 0, v[178:179]
	s_add_i32 m0, s29, 0xe000
	s_nop 0
	global_load_lds_dwordx4 v[200:201], off
	s_waitcnt vmcnt(8)
	s_waitcnt lgkmcnt(0)
	s_setprio 1
	s_barrier
	v_mfma_f32_16x16x32_bf16 v[124:127], v[128:131], v[192:195], 0
	v_mfma_f32_16x16x32_bf16 v[120:123], v[136:139], v[192:195], 0
	v_mfma_f32_16x16x32_bf16 v[108:111], v[128:131], v[204:207], 0
	v_mfma_f32_16x16x32_bf16 v[104:107], v[136:139], v[204:207], 0
	v_mfma_f32_16x16x32_bf16 v[92:95], v[128:131], v[212:215], 0
	v_mfma_f32_16x16x32_bf16 v[88:91], v[136:139], v[212:215], 0
	v_mfma_f32_16x16x32_bf16 v[76:79], v[128:131], v[220:223], 0
	v_mfma_f32_16x16x32_bf16 v[72:75], v[136:139], v[220:223], 0
	v_mfma_f32_16x16x32_bf16 v[124:127], v[132:135], v[196:199], v[124:127]
	v_mfma_f32_16x16x32_bf16 v[120:123], v[140:143], v[196:199], v[120:123]
	v_mfma_f32_16x16x32_bf16 v[108:111], v[132:135], v[208:211], v[108:111]
	v_mfma_f32_16x16x32_bf16 v[104:107], v[140:143], v[208:211], v[104:107]
	v_mfma_f32_16x16x32_bf16 v[92:95], v[132:135], v[216:219], v[92:95]
	v_mfma_f32_16x16x32_bf16 v[88:91], v[140:143], v[216:219], v[88:91]
	v_mfma_f32_16x16x32_bf16 v[76:79], v[132:135], v[224:227], v[76:79]
	v_mfma_f32_16x16x32_bf16 v[72:75], v[140:143], v[224:227], v[72:75]
	s_setprio 0
	s_setprio 1
	v_mfma_f32_16x16x32_bf16 v[116:119], v[144:147], v[192:195], 0
	v_mfma_f32_16x16x32_bf16 v[112:115], v[184:187], v[192:195], 0
	v_mfma_f32_16x16x32_bf16 v[100:103], v[144:147], v[204:207], 0
	v_mfma_f32_16x16x32_bf16 v[96:99], v[184:187], v[204:207], 0
	v_mfma_f32_16x16x32_bf16 v[84:87], v[144:147], v[212:215], 0
	v_mfma_f32_16x16x32_bf16 v[80:83], v[184:187], v[212:215], 0
	v_mfma_f32_16x16x32_bf16 v[68:71], v[144:147], v[220:223], 0
	v_mfma_f32_16x16x32_bf16 v[64:67], v[184:187], v[220:223], 0
	v_mfma_f32_16x16x32_bf16 v[116:119], v[148:151], v[196:199], v[116:119]
	v_mfma_f32_16x16x32_bf16 v[112:115], v[188:191], v[196:199], v[112:115]
	v_mfma_f32_16x16x32_bf16 v[100:103], v[148:151], v[208:211], v[100:103]
	v_mfma_f32_16x16x32_bf16 v[96:99], v[188:191], v[208:211], v[96:99]
	v_mfma_f32_16x16x32_bf16 v[84:87], v[148:151], v[216:219], v[84:87]
	v_mfma_f32_16x16x32_bf16 v[80:83], v[188:191], v[216:219], v[80:83]
	v_mfma_f32_16x16x32_bf16 v[68:71], v[148:151], v[224:227], v[68:71]
	v_mfma_f32_16x16x32_bf16 v[64:67], v[188:191], v[224:227], v[64:67]
	s_barrier
	s_setprio 0
	s_add_i32 s55, s40, s28
	v_lshl_add_u64 v[200:201], s[24:25], 0, v[166:167]
	s_mov_b32 m0, s55
	ds_read_b128 v[192:195], v202 offset:16384
	ds_read_b128 v[196:199], v202 offset:17408
	ds_read_b128 v[204:207], v202 offset:18432
	ds_read_b128 v[208:211], v202 offset:19456
	ds_read_b128 v[212:215], v202 offset:20480
	ds_read_b128 v[216:219], v202 offset:21504
	ds_read_b128 v[220:223], v202 offset:22528
	ds_read_b128 v[224:227], v202 offset:23552
	global_load_lds_dwordx4 v[200:201], off
	s_add_i32 m0, s55, 0x2000
	s_add_u32 s56, s24, 0xb0000
	v_lshl_add_u64 v[228:229], s[24:25], 0, v[170:171]
	s_addc_u32 s57, s25, 0
	s_add_i32 s55, s41, s28
	global_load_lds_dwordx4 v[228:229], off
	v_lshl_add_u64 v[248:249], s[56:57], 0, v[166:167]
	s_mov_b32 m0, s55
	v_lshl_add_u64 v[250:251], s[26:27], 0, v[168:169]
	global_load_lds_dwordx4 v[248:249], off
	v_lshl_add_u64 v[248:249], s[56:57], 0, v[170:171]
	s_add_i32 m0, s55, 0x2000
	s_nop 0
	global_load_lds_dwordx4 v[248:249], off
	v_lshl_add_u64 v[248:249], s[26:27], 0, v[164:165]
	s_mov_b32 m0, s29
	s_nop 0
	global_load_lds_dwordx4 v[248:249], off
	s_mov_b32 m0, s30
	s_nop 0
	global_load_lds_dwordx4 v[250:251], off
	s_waitcnt vmcnt(8)
	s_waitcnt lgkmcnt(0)
	s_setprio 1
	s_barrier
; #define PG8_STAGE(bufoff, gbase, voff) do { _Pragma("unroll") for (int _i = 0; _i < 2; ++_i) \
;         __builtin_amdgcn_global_load_lds((const unsigned*)((const char*)(gbase) + (voff)[_i]), (PG8_LAS unsigned*)(lds + (bufoff) + ldsw + _i * 8192), 16, 0, 0); } while (0)
; #define PG8_LDA(dst, b, h) do { _Pragma("unroll") for (int m = 0; m < 4; ++m) _Pragma("unroll") for (int k = 0; k < 2; ++k) dst[m][k] = *(const PG8_LAS bf16x8*)(lds + PG8_SA(b, h) + aoff + m * 2048 + k * 1024); } while (0)
; #define PG8_LDB(dst, b, h) do { _Pragma("unroll") for (int n = 0; n < 2; ++n) _Pragma("unroll") for (int k = 0; k < 2; ++k) dst[n][k] = *(const PG8_LAS bf16x8*)(lds + PG8_SB(b, h) + boff + n * 2048 + k * 1024); } while (0)
; #define PG8_MMA(ai, bj, At, Bt) do { __builtin_amdgcn_s_setprio(1); _Pragma("unroll") for (int m = 0; m < 4; ++m) _Pragma("unroll") for (int n = 0; n < 2; ++n) _Pragma("unroll") for (int k = 0; k < 2; ++k) \
;         acc[ai][bj][m][n] = __builtin_amdgcn_mfma_f32_16x16x32_bf16(Bt[n][k], At[m][k], acc[ai][bj][m][n], 0, 0, 0); __builtin_amdgcn_s_setprio(0); } while (0)
; #define PG8_WAIT_V(n) asm volatile("s_waitcnt vmcnt(" #n ")" ::: "memory")
; #define PG8_WAIT_L(n) asm volatile("s_waitcnt lgkmcnt(" #n ")" ::: "memory")
; #define PG8_BAR __builtin_amdgcn_s_barrier()
; #define PG8_SCHED __builtin_amdgcn_sched_barrier(0)
; template <class Epi, class Sched, bool ALIGN_EPI = false, bool SP2 = false>
; __device__ __forceinline__ void gemm_phase(PG8_LAS unsigned char* lds, const Gemm g, const Sched& S, const Epi& E) {
;     ...
;             PG8_WAIT_V(8); PG8_WAIT_L(0); PG8_BAR; PG8_MMA(1, 0, At, B0); PG8_MMA(1, 1, At, B1); PG8_BAR; PG8_SCHED;
;             PG8_LDB(B0, 1, 0); PG8_LDB(B1, 1, 1); PG8_SCHED; PG8_LDA(At, 1, 0); PG8_STAGE(PG8_SA(0, 1), a2 + hstep, voffA);
;             PG8_WAIT_V(8); PG8_WAIT_L(0); PG8_BAR; PG8_MMA(0, 0, At, B0); PG8_MMA(0, 1, At, B1); PG8_BAR; PG8_SCHED;
	v_mfma_f32_16x16x32_bf16 v[60:63], v[128:131], v[192:195], 0
	v_mfma_f32_16x16x32_bf16 v[56:59], v[136:139], v[192:195], 0
	v_mfma_f32_16x16x32_bf16 v[44:47], v[128:131], v[204:207], 0
	v_mfma_f32_16x16x32_bf16 v[40:43], v[136:139], v[204:207], 0
	v_mfma_f32_16x16x32_bf16 v[28:31], v[128:131], v[212:215], 0
	v_mfma_f32_16x16x32_bf16 v[24:27], v[136:139], v[212:215], 0
	v_mfma_f32_16x16x32_bf16 v[12:15], v[128:131], v[220:223], 0
	v_mfma_f32_16x16x32_bf16 v[8:11], v[136:139], v[220:223], 0
	v_mfma_f32_16x16x32_bf16 v[60:63], v[132:135], v[196:199], v[60:63]
	v_mfma_f32_16x16x32_bf16 v[56:59], v[140:143], v[196:199], v[56:59]
	v_mfma_f32_16x16x32_bf16 v[44:47], v[132:135], v[208:211], v[44:47]
	v_mfma_f32_16x16x32_bf16 v[40:43], v[140:143], v[208:211], v[40:43]
	v_mfma_f32_16x16x32_bf16 v[28:31], v[132:135], v[216:219], v[28:31]
	v_mfma_f32_16x16x32_bf16 v[24:27], v[140:143], v[216:219], v[24:27]
	v_mfma_f32_16x16x32_bf16 v[12:15], v[132:135], v[224:227], v[12:15]
	v_mfma_f32_16x16x32_bf16 v[8:11], v[140:143], v[224:227], v[8:11]
	s_setprio 0
	s_setprio 1
	v_mfma_f32_16x16x32_bf16 v[52:55], v[144:147], v[192:195], 0
	v_mfma_f32_16x16x32_bf16 v[48:51], v[184:187], v[192:195], 0
	v_mfma_f32_16x16x32_bf16 v[36:39], v[144:147], v[204:207], 0
	v_mfma_f32_16x16x32_bf16 v[32:35], v[184:187], v[204:207], 0
	v_mfma_f32_16x16x32_bf16 v[20:23], v[144:147], v[212:215], 0
	v_mfma_f32_16x16x32_bf16 v[16:19], v[184:187], v[212:215], 0
	v_mfma_f32_16x16x32_bf16 v[4:7], v[144:147], v[220:223], 0
	v_mfma_f32_16x16x32_bf16 v[0:3], v[184:187], v[220:223], 0
	v_mfma_f32_16x16x32_bf16 v[52:55], v[148:151], v[196:199], v[52:55]
	v_mfma_f32_16x16x32_bf16 v[48:51], v[188:191], v[196:199], v[48:51]
	v_mfma_f32_16x16x32_bf16 v[36:39], v[148:151], v[208:211], v[36:39]
	v_mfma_f32_16x16x32_bf16 v[32:35], v[188:191], v[208:211], v[32:35]
	v_mfma_f32_16x16x32_bf16 v[20:23], v[148:151], v[216:219], v[20:23]
	v_mfma_f32_16x16x32_bf16 v[16:19], v[188:191], v[216:219], v[16:19]
	v_mfma_f32_16x16x32_bf16 v[4:7], v[148:151], v[224:227], v[4:7]
	v_mfma_f32_16x16x32_bf16 v[0:3], v[188:191], v[224:227], v[0:3]
	s_barrier
	s_setprio 0
	s_add_i32 s55, 0, 0x18000
	s_add_i32 s56, 0, 0x1c000
	v_add_u32_e32 v140, s55, v159
	v_add_u32_e32 v188, s56, v159
	ds_read_b128 v[128:131], v140
	ds_read_b128 v[132:135], v140 offset:1024
	ds_read_b128 v[136:139], v140 offset:2048
	ds_read_b128 v[140:143], v140 offset:3072
	ds_read_b128 v[144:147], v188
	ds_read_b128 v[148:151], v188 offset:1024
	ds_read_b128 v[184:187], v188 offset:2048
	ds_read_b128 v[188:191], v188 offset:3072
	s_add_u32 s26, s26, 0xb0000
	s_addc_u32 s27, s27, 0
	s_mov_b32 m0, s31
	v_lshl_add_u64 v[252:253], s[26:27], 0, v[164:165]
	ds_read_b128 v[192:195], v202 offset:32768
	ds_read_b128 v[196:199], v202 offset:33792
	ds_read_b128 v[204:207], v202 offset:34816
	ds_read_b128 v[208:211], v202 offset:35840
	ds_read_b128 v[212:215], v202 offset:36864
	ds_read_b128 v[216:219], v202 offset:37888
	ds_read_b128 v[220:223], v202 offset:38912
	ds_read_b128 v[224:227], v202 offset:39936
	global_load_lds_dwordx4 v[252:253], off
	v_lshl_add_u64 v[252:253], s[26:27], 0, v[168:169]
	s_mov_b32 m0, s33
	s_nop 0
	global_load_lds_dwordx4 v[252:253], off
	s_waitcnt vmcnt(8)
	s_waitcnt lgkmcnt(0)
	s_setprio 1
	s_barrier
	v_mfma_f32_16x16x32_bf16 v[124:127], v[128:131], v[192:195], v[124:127]
	v_mfma_f32_16x16x32_bf16 v[120:123], v[136:139], v[192:195], v[120:123]
	v_mfma_f32_16x16x32_bf16 v[108:111], v[128:131], v[204:207], v[108:111]
	v_mfma_f32_16x16x32_bf16 v[104:107], v[136:139], v[204:207], v[104:107]
	v_mfma_f32_16x16x32_bf16 v[92:95], v[128:131], v[212:215], v[92:95]
	v_mfma_f32_16x16x32_bf16 v[88:91], v[136:139], v[212:215], v[88:91]
	v_mfma_f32_16x16x32_bf16 v[76:79], v[128:131], v[220:223], v[76:79]
	v_mfma_f32_16x16x32_bf16 v[72:75], v[136:139], v[220:223], v[72:75]
	v_mfma_f32_16x16x32_bf16 v[124:127], v[132:135], v[196:199], v[124:127]
	v_mfma_f32_16x16x32_bf16 v[120:123], v[140:143], v[196:199], v[120:123]
	v_mfma_f32_16x16x32_bf16 v[108:111], v[132:135], v[208:211], v[108:111]
	v_mfma_f32_16x16x32_bf16 v[104:107], v[140:143], v[208:211], v[104:107]
	v_mfma_f32_16x16x32_bf16 v[92:95], v[132:135], v[216:219], v[92:95]
	v_mfma_f32_16x16x32_bf16 v[88:91], v[140:143], v[216:219], v[88:91]
	v_mfma_f32_16x16x32_bf16 v[76:79], v[132:135], v[224:227], v[76:79]
	v_mfma_f32_16x16x32_bf16 v[72:75], v[140:143], v[224:227], v[72:75]
	s_setprio 0
	s_setprio 1
	v_mfma_f32_16x16x32_bf16 v[116:119], v[144:147], v[192:195], v[116:119]
	v_mfma_f32_16x16x32_bf16 v[112:115], v[184:187], v[192:195], v[112:115]
	v_mfma_f32_16x16x32_bf16 v[100:103], v[144:147], v[204:207], v[100:103]
	v_mfma_f32_16x16x32_bf16 v[96:99], v[184:187], v[204:207], v[96:99]
	v_mfma_f32_16x16x32_bf16 v[84:87], v[144:147], v[212:215], v[84:87]
	v_mfma_f32_16x16x32_bf16 v[80:83], v[184:187], v[212:215], v[80:83]
	v_mfma_f32_16x16x32_bf16 v[68:71], v[144:147], v[220:223], v[68:71]
	v_mfma_f32_16x16x32_bf16 v[64:67], v[184:187], v[220:223], v[64:67]
	v_mfma_f32_16x16x32_bf16 v[116:119], v[148:151], v[196:199], v[116:119]
	v_mfma_f32_16x16x32_bf16 v[112:115], v[188:191], v[196:199], v[112:115]
	v_mfma_f32_16x16x32_bf16 v[100:103], v[148:151], v[208:211], v[100:103]
	v_mfma_f32_16x16x32_bf16 v[96:99], v[188:191], v[208:211], v[96:99]
	v_mfma_f32_16x16x32_bf16 v[84:87], v[148:151], v[216:219], v[84:87]
	v_mfma_f32_16x16x32_bf16 v[80:83], v[188:191], v[216:219], v[80:83]
	v_mfma_f32_16x16x32_bf16 v[68:71], v[148:151], v[224:227], v[68:71]
	v_mfma_f32_16x16x32_bf16 v[64:67], v[188:191], v[224:227], v[64:67]
	s_barrier
; #define PG8_STAGE(bufoff, gbase, voff) do { _Pragma("unroll") for (int _i = 0; _i < 2; ++_i) \
;         __builtin_amdgcn_global_load_lds((const unsigned*)((const char*)(gbase) + (voff)[_i]), (PG8_LAS unsigned*)(lds + (bufoff) + ldsw + _i * 8192), 16, 0, 0); } while (0)
; #define PG8_LDA(dst, b, h) do { _Pragma("unroll") for (int m = 0; m < 4; ++m) _Pragma("unroll") for (int k = 0; k < 2; ++k) dst[m][k] = *(const PG8_LAS bf16x8*)(lds + PG8_SA(b, h) + aoff + m * 2048 + k * 1024); } while (0)
; #define PG8_MMA(ai, bj, At, Bt) do { __builtin_amdgcn_s_setprio(1); _Pragma("unroll") for (int m = 0; m < 4; ++m) _Pragma("unroll") for (int n = 0; n < 2; ++n) _Pragma("unroll") for (int k = 0; k < 2; ++k) \
;         acc[ai][bj][m][n] = __builtin_amdgcn_mfma_f32_16x16x32_bf16(Bt[n][k], At[m][k], acc[ai][bj][m][n], 0, 0, 0); __builtin_amdgcn_s_setprio(0); } while (0)
; #define PG8_WAIT_V(n) asm volatile("s_waitcnt vmcnt(" #n ")" ::: "memory")
; #define PG8_WAIT_L(n) asm volatile("s_waitcnt lgkmcnt(" #n ")" ::: "memory")
; #define PG8_BAR __builtin_amdgcn_s_barrier()
; #define PG8_SCHED __builtin_amdgcn_sched_barrier(0)
; template <class Epi, class Sched, bool ALIGN_EPI = false, bool SP2 = false>
; __device__ __forceinline__ void gemm_phase(PG8_LAS unsigned char* lds, const Gemm g, const Sched& S, const Epi& E) {
;     ...
;         for (int t = 0; t < nt; t += 2) {
;     ...
;             PG8_LDA(At, 1, 1); PG8_STAGE(PG8_SB(1, 0), b3, voffB); PG8_STAGE(PG8_SB(1, 1), b3 + hstep, voffB); PG8_STAGE(PG8_SA(1, 0), a3, voffA);
;             PG8_WAIT_V(8); PG8_WAIT_L(0); PG8_BAR; PG8_MMA(1, 0, At, B0); PG8_MMA(1, 1, At, B1); PG8_BAR; PG8_SCHED;
	s_setprio 0
	s_add_i32 s26, s55, s28
	v_lshl_add_u64 v[200:201], v[200:201], 0, s[12:13]
	s_mov_b32 m0, s26
	ds_read_b128 v[192:195], v202 offset:49152
	ds_read_b128 v[196:199], v202 offset:50176
	ds_read_b128 v[204:207], v202 offset:51200
	ds_read_b128 v[208:211], v202 offset:52224
	ds_read_b128 v[212:215], v202 offset:53248
	ds_read_b128 v[216:219], v202 offset:54272
	ds_read_b128 v[220:223], v202 offset:55296
	ds_read_b128 v[224:227], v202 offset:56320
	global_load_lds_dwordx4 v[200:201], off
	s_add_i32 m0, s26, 0x2000
	s_add_u32 s24, s24, 0xb0080
	v_lshl_add_u64 v[200:201], v[228:229], 0, s[12:13]
	s_addc_u32 s25, s25, 0
	s_add_i32 s26, s56, s28
	global_load_lds_dwordx4 v[200:201], off
	v_lshl_add_u64 v[200:201], s[24:25], 0, v[166:167]
	s_mov_b32 m0, s26
	s_nop 0
	global_load_lds_dwordx4 v[200:201], off
	v_lshl_add_u64 v[200:201], s[24:25], 0, v[170:171]
	s_add_i32 m0, s26, 0x2000
	s_nop 0
	global_load_lds_dwordx4 v[200:201], off
	v_lshl_add_u64 v[200:201], v[248:249], 0, s[12:13]
	s_mov_b32 m0, s35
	s_nop 0
	global_load_lds_dwordx4 v[200:201], off
	v_lshl_add_u64 v[200:201], v[250:251], 0, s[12:13]
	s_mov_b32 m0, s36
	s_nop 0
	global_load_lds_dwordx4 v[200:201], off
	s_waitcnt vmcnt(8)
	s_waitcnt lgkmcnt(0)
	s_setprio 1
	s_barrier
	v_mfma_f32_16x16x32_bf16 v[60:63], v[128:131], v[192:195], v[60:63]
	v_mfma_f32_16x16x32_bf16 v[56:59], v[136:139], v[192:195], v[56:59]
	v_mfma_f32_16x16x32_bf16 v[44:47], v[128:131], v[204:207], v[44:47]
	v_mfma_f32_16x16x32_bf16 v[40:43], v[136:139], v[204:207], v[40:43]
	v_mfma_f32_16x16x32_bf16 v[28:31], v[128:131], v[212:215], v[28:31]
	v_mfma_f32_16x16x32_bf16 v[24:27], v[136:139], v[212:215], v[24:27]
	v_mfma_f32_16x16x32_bf16 v[12:15], v[128:131], v[220:223], v[12:15]
	v_mfma_f32_16x16x32_bf16 v[8:11], v[136:139], v[220:223], v[8:11]
	v_mfma_f32_16x16x32_bf16 v[60:63], v[132:135], v[196:199], v[60:63]
	v_mfma_f32_16x16x32_bf16 v[56:59], v[140:143], v[196:199], v[56:59]
	v_mfma_f32_16x16x32_bf16 v[44:47], v[132:135], v[208:211], v[44:47]
	v_mfma_f32_16x16x32_bf16 v[40:43], v[140:143], v[208:211], v[40:43]
	v_mfma_f32_16x16x32_bf16 v[28:31], v[132:135], v[216:219], v[28:31]
	v_mfma_f32_16x16x32_bf16 v[24:27], v[140:143], v[216:219], v[24:27]
	v_mfma_f32_16x16x32_bf16 v[12:15], v[132:135], v[224:227], v[12:15]
	v_mfma_f32_16x16x32_bf16 v[8:11], v[140:143], v[224:227], v[8:11]
	s_setprio 0
	s_setprio 1
	v_mfma_f32_16x16x32_bf16 v[52:55], v[144:147], v[192:195], v[52:55]
	v_mfma_f32_16x16x32_bf16 v[48:51], v[184:187], v[192:195], v[48:51]
	v_mfma_f32_16x16x32_bf16 v[36:39], v[144:147], v[204:207], v[36:39]
	v_mfma_f32_16x16x32_bf16 v[32:35], v[184:187], v[204:207], v[32:35]
	v_mfma_f32_16x16x32_bf16 v[20:23], v[144:147], v[212:215], v[20:23]
	v_mfma_f32_16x16x32_bf16 v[16:19], v[184:187], v[212:215], v[16:19]
	v_mfma_f32_16x16x32_bf16 v[4:7], v[144:147], v[220:223], v[4:7]
	v_mfma_f32_16x16x32_bf16 v[0:3], v[184:187], v[220:223], v[0:3]
	v_mfma_f32_16x16x32_bf16 v[52:55], v[148:151], v[196:199], v[52:55]
	v_mfma_f32_16x16x32_bf16 v[48:51], v[188:191], v[196:199], v[48:51]
	v_mfma_f32_16x16x32_bf16 v[36:39], v[148:151], v[208:211], v[36:39]
	v_mfma_f32_16x16x32_bf16 v[32:35], v[188:191], v[208:211], v[32:35]
	v_mfma_f32_16x16x32_bf16 v[20:23], v[148:151], v[216:219], v[20:23]
	v_mfma_f32_16x16x32_bf16 v[16:19], v[188:191], v[216:219], v[16:19]
	v_mfma_f32_16x16x32_bf16 v[4:7], v[148:151], v[224:227], v[4:7]
	v_mfma_f32_16x16x32_bf16 v[0:3], v[188:191], v[224:227], v[0:3]
	s_barrier
	s_setprio 0
	s_add_i32 s54, s54, 2
	s_add_u32 s20, s20, 0x100
	s_addc_u32 s21, s21, 0
	s_add_u32 s46, s46, 0x100
	s_addc_u32 s47, s47, 0
	s_cmp_gt_u32 s54, 41
	s_cbranch_scc1 .Lpeel_done_g1

; #define PG8_BAR __builtin_amdgcn_s_barrier()
; template <class Epi, class Sched, bool ALIGN_EPI = false, bool SP2 = false>
; __device__ __forceinline__ void gemm_phase(PG8_LAS unsigned char* lds, const Gemm g, const Sched& S, const Epi& E) {
;     ...
;         if constexpr (ALIGN_EPI) { if (wr == 0) PG8_BAR; }
;         if constexpr (!Epi::AFTER_DRAIN) { E(acc, cur, wr, wc, fr, fq); S.done(cur); }
.Lpeel_done_g1:
	s_and_b64 vcc, exec, s[16:17]
	s_cbranch_vccz .LBB0_375
	s_barrier

; #define PG8_STAGE(bufoff, gbase, voff) do { _Pragma("unroll") for (int _i = 0; _i < 2; ++_i) \
;         __builtin_amdgcn_global_load_lds((const unsigned*)((const char*)(gbase) + (voff)[_i]), (PG8_LAS unsigned*)(lds + (bufoff) + ldsw + _i * 8192), 16, 0, 0); } while (0)
; #define PG8_LDA(dst, b, h) do { _Pragma("unroll") for (int m = 0; m < 4; ++m) _Pragma("unroll") for (int k = 0; k < 2; ++k) dst[m][k] = *(const PG8_LAS bf16x8*)(lds + PG8_SA(b, h) + aoff + m * 2048 + k * 1024); } while (0)
; #define PG8_LDB(dst, b, h) do { _Pragma("unroll") for (int n = 0; n < 2; ++n) _Pragma("unroll") for (int k = 0; k < 2; ++k) dst[n][k] = *(const PG8_LAS bf16x8*)(lds + PG8_SB(b, h) + boff + n * 2048 + k * 1024); } while (0)
; #define PG8_WAIT_V(n) asm volatile("s_waitcnt vmcnt(" #n ")" ::: "memory")
; #define PG8_WAIT_L(n) asm volatile("s_waitcnt lgkmcnt(" #n ")" ::: "memory")
; #define PG8_BAR __builtin_amdgcn_s_barrier()
; #define PG8_SCHED __builtin_amdgcn_sched_barrier(0)
; template <class Epi, class Sched, bool ALIGN_EPI = false, bool SP2 = false>
; __device__ __forceinline__ void gemm_phase(PG8_LAS unsigned char* lds, const Gemm g, const Sched& S, const Epi& E) {
;     ...
;         const bool has_next = S.next(ui + 1, nxt);
;         const char* nA = has_next ? (const char*)g.A + (size_t)nxt.pm * tstep : cA; const char* nB = has_next ? (const char*)g.Bt + (size_t)nxt.pn * tstep : cB;
;         for (int t = 0; t < nt; t += 2) {
;             const bool last = (t == nt - 2);
;             const char* a1 = cA + (size_t)(t + 1) * kstep;
;             const char* a2 = last ? nA : cA + (size_t)(t + 2) * kstep; const char* b2 = last ? nB : cB + (size_t)(t + 2) * kstep;
;             const char* a3 = a2 + kstep; const char* b3 = b2 + kstep;
;             if (last && has_next) S.a_ready(nxt);
;             if constexpr (SP2) {
;             PG8_LDB(B0, 0, 0); PG8_LDB(B1, 0, 1); PG8_SCHED; PG8_LDA(At, 0, 0); PG8_STAGE(PG8_SA(1, 1), a1 + hstep, voffA);
;             PG8_WAIT_V(8); PG8_WAIT_L(0); PG8_BAR; PG8_MMA(0, 0, At, B0); PG8_MMA(0, 1, At, B1); PG8_BAR; PG8_SCHED;
;             PG8_LDA(At, 0, 1); PG8_STAGE(PG8_SB(0, 0), b2, voffB); PG8_STAGE(PG8_SB(0, 1), b2 + hstep, voffB); PG8_STAGE(PG8_SA(0, 0), a2, voffA);
;             PG8_WAIT_V(8); PG8_WAIT_L(0); PG8_BAR; PG8_MMA(1, 0, At, B0); PG8_MMA(1, 1, At, B1); PG8_BAR; PG8_SCHED;
.LBB0_463:
	s_ashr_i32 s21, s20, 31
	s_lshl_b64 s[24:25], s[20:21], 19
	s_add_u32 s24, s76, s24
	s_addc_u32 s25, s77, s25
	s_and_b64 s[26:27], s[10:11], exec
	s_cselect_b32 s13, s25, s1
	s_cselect_b32 s21, s24, s0
	s_ashr_i32 s19, s18, 31
	s_lshl_b64 s[26:27], s[18:19], 19
	s_add_u32 s26, s33, s26
	s_addc_u32 s27, s36, s27
	s_and_b64 s[34:35], s[10:11], exec
	s_cselect_b32 s19, s27, s31
	s_cselect_b32 s58, s26, s30
	s_add_u32 s0, s0, 0x40080
	s_addc_u32 s1, s1, 0
	s_add_u32 s59, s30, 0x100
	s_addc_u32 s80, s31, 0
	s_mov_b32 s81, -2
	ds_read_b128 v[128:131], v149
	ds_read_b128 v[132:135], v149 offset:1024
	ds_read_b128 v[140:143], v149 offset:2048
	ds_read_b128 v[176:179], v149 offset:3072
	ds_read_b128 v[180:183], v150
	ds_read_b128 v[184:187], v150 offset:1024
	ds_read_b128 v[188:191], v150 offset:2048
	ds_read_b128 v[192:195], v150 offset:3072
	s_add_u32 s30, s0, 0xfffc0080
	s_addc_u32 s31, s1, -1
	s_cmp_eq_u32 s81, 12
	s_cselect_b32 s35, s13, s31
	s_cselect_b32 s34, s21, s30
	s_cselect_b32 s31, s19, s80
	s_cselect_b32 s30, s58, s59
	v_lshl_add_u64 v[228:229], s[0:1], 0, v[136:137]
	s_add_i32 m0, s29, 0xc000
	ds_read_b128 v[196:199], v151
	ds_read_b128 v[200:203], v151 offset:1024
	ds_read_b128 v[204:207], v151 offset:2048
	ds_read_b128 v[208:211], v151 offset:3072
	ds_read_b128 v[212:215], v151 offset:4096
	ds_read_b128 v[216:219], v151 offset:5120
	ds_read_b128 v[220:223], v151 offset:6144
	ds_read_b128 v[224:227], v151 offset:7168
	global_load_lds_dwordx4 v[228:229], off
	v_lshl_add_u64 v[228:229], s[0:1], 0, v[138:139]
	s_add_i32 m0, s29, 0xe000
	s_nop 0
	global_load_lds_dwordx4 v[228:229], off
	s_waitcnt vmcnt(8)
	s_waitcnt lgkmcnt(0)
	s_setprio 1
	s_barrier
	v_mfma_f32_16x16x32_bf16 v[124:127], v[128:131], v[196:199], 0
	v_mfma_f32_16x16x32_bf16 v[120:123], v[140:143], v[196:199], 0
	v_mfma_f32_16x16x32_bf16 v[108:111], v[128:131], v[204:207], 0
	v_mfma_f32_16x16x32_bf16 v[104:107], v[140:143], v[204:207], 0
	v_mfma_f32_16x16x32_bf16 v[92:95], v[128:131], v[212:215], 0
	v_mfma_f32_16x16x32_bf16 v[88:91], v[140:143], v[212:215], 0
	v_mfma_f32_16x16x32_bf16 v[76:79], v[128:131], v[220:223], 0
	v_mfma_f32_16x16x32_bf16 v[72:75], v[140:143], v[220:223], 0
	v_mfma_f32_16x16x32_bf16 v[124:127], v[132:135], v[200:203], v[124:127]
	v_mfma_f32_16x16x32_bf16 v[120:123], v[176:179], v[200:203], v[120:123]
	v_mfma_f32_16x16x32_bf16 v[108:111], v[132:135], v[208:211], v[108:111]
	v_mfma_f32_16x16x32_bf16 v[104:107], v[176:179], v[208:211], v[104:107]
	v_mfma_f32_16x16x32_bf16 v[92:95], v[132:135], v[216:219], v[92:95]
	v_mfma_f32_16x16x32_bf16 v[88:91], v[176:179], v[216:219], v[88:91]
	v_mfma_f32_16x16x32_bf16 v[76:79], v[132:135], v[224:227], v[76:79]
	v_mfma_f32_16x16x32_bf16 v[72:75], v[176:179], v[224:227], v[72:75]
	s_setprio 0
	s_setprio 1
	v_mfma_f32_16x16x32_bf16 v[116:119], v[180:183], v[196:199], 0
	v_mfma_f32_16x16x32_bf16 v[112:115], v[188:191], v[196:199], 0
	v_mfma_f32_16x16x32_bf16 v[100:103], v[180:183], v[204:207], 0
	v_mfma_f32_16x16x32_bf16 v[96:99], v[188:191], v[204:207], 0
	v_mfma_f32_16x16x32_bf16 v[84:87], v[180:183], v[212:215], 0
	v_mfma_f32_16x16x32_bf16 v[80:83], v[188:191], v[212:215], 0
	v_mfma_f32_16x16x32_bf16 v[68:71], v[180:183], v[220:223], 0
	v_mfma_f32_16x16x32_bf16 v[64:67], v[188:191], v[220:223], 0
	v_mfma_f32_16x16x32_bf16 v[116:119], v[184:187], v[200:203], v[116:119]
	v_mfma_f32_16x16x32_bf16 v[112:115], v[192:195], v[200:203], v[112:115]
	v_mfma_f32_16x16x32_bf16 v[100:103], v[184:187], v[208:211], v[100:103]
	v_mfma_f32_16x16x32_bf16 v[96:99], v[192:195], v[208:211], v[96:99]
	v_mfma_f32_16x16x32_bf16 v[84:87], v[184:187], v[216:219], v[84:87]
	v_mfma_f32_16x16x32_bf16 v[80:83], v[192:195], v[216:219], v[80:83]
	v_mfma_f32_16x16x32_bf16 v[68:71], v[184:187], v[224:227], v[68:71]
	v_mfma_f32_16x16x32_bf16 v[64:67], v[192:195], v[224:227], v[64:67]
	s_barrier
	s_setprio 0
	s_add_i32 s82, s46, s3
	v_lshl_add_u64 v[228:229], s[30:31], 0, v[158:159]
	s_mov_b32 m0, s82
	ds_read_b128 v[196:199], v151 offset:16384
	ds_read_b128 v[200:203], v151 offset:17408
	ds_read_b128 v[204:207], v151 offset:18432
	ds_read_b128 v[208:211], v151 offset:19456
	ds_read_b128 v[212:215], v151 offset:20480
	ds_read_b128 v[216:219], v151 offset:21504
	ds_read_b128 v[220:223], v151 offset:22528
	ds_read_b128 v[224:227], v151 offset:23552
	global_load_lds_dwordx4 v[228:229], off
	s_add_i32 m0, s82, 0x2000
	s_add_u32 s82, s30, 0x40000
	v_lshl_add_u64 v[248:249], s[30:31], 0, v[162:163]
	s_addc_u32 s83, s31, 0
	s_add_i32 s84, s47, s3
	global_load_lds_dwordx4 v[248:249], off
	v_lshl_add_u64 v[250:251], s[82:83], 0, v[158:159]
	s_mov_b32 m0, s84
	v_lshl_add_u64 v[252:253], s[34:35], 0, v[160:161]
	global_load_lds_dwordx4 v[250:251], off
	v_lshl_add_u64 v[250:251], s[82:83], 0, v[162:163]
	s_add_i32 m0, s84, 0x2000
	s_nop 0
	global_load_lds_dwordx4 v[250:251], off
	v_lshl_add_u64 v[250:251], s[34:35], 0, v[156:157]
	s_mov_b32 m0, s29
	s_nop 0
	global_load_lds_dwordx4 v[250:251], off
	s_mov_b32 m0, s37
	s_nop 0
	global_load_lds_dwordx4 v[252:253], off
	s_waitcnt vmcnt(8)
	s_waitcnt lgkmcnt(0)
	s_setprio 1
	s_barrier
; #define PG8_STAGE(bufoff, gbase, voff) do { _Pragma("unroll") for (int _i = 0; _i < 2; ++_i) \
;         __builtin_amdgcn_global_load_lds((const unsigned*)((const char*)(gbase) + (voff)[_i]), (PG8_LAS unsigned*)(lds + (bufoff) + ldsw + _i * 8192), 16, 0, 0); } while (0)
; #define PG8_LDA(dst, b, h) do { _Pragma("unroll") for (int m = 0; m < 4; ++m) _Pragma("unroll") for (int k = 0; k < 2; ++k) dst[m][k] = *(const PG8_LAS bf16x8*)(lds + PG8_SA(b, h) + aoff + m * 2048 + k * 1024); } while (0)
; #define PG8_LDB(dst, b, h) do { _Pragma("unroll") for (int n = 0; n < 2; ++n) _Pragma("unroll") for (int k = 0; k < 2; ++k) dst[n][k] = *(const PG8_LAS bf16x8*)(lds + PG8_SB(b, h) + boff + n * 2048 + k * 1024); } while (0)
; #define PG8_MMA(ai, bj, At, Bt) do { __builtin_amdgcn_s_setprio(1); _Pragma("unroll") for (int m = 0; m < 4; ++m) _Pragma("unroll") for (int n = 0; n < 2; ++n) _Pragma("unroll") for (int k = 0; k < 2; ++k) \
;         acc[ai][bj][m][n] = __builtin_amdgcn_mfma_f32_16x16x32_bf16(Bt[n][k], At[m][k], acc[ai][bj][m][n], 0, 0, 0); __builtin_amdgcn_s_setprio(0); } while (0)
; #define PG8_WAIT_V(n) asm volatile("s_waitcnt vmcnt(" #n ")" ::: "memory")
; #define PG8_WAIT_L(n) asm volatile("s_waitcnt lgkmcnt(" #n ")" ::: "memory")
; #define PG8_BAR __builtin_amdgcn_s_barrier()
; #define PG8_SCHED __builtin_amdgcn_sched_barrier(0)
; template <class Epi, class Sched, bool ALIGN_EPI = false, bool SP2 = false>
; __device__ __forceinline__ void gemm_phase(PG8_LAS unsigned char* lds, const Gemm g, const Sched& S, const Epi& E) {
;     ...
;             PG8_WAIT_V(8); PG8_WAIT_L(0); PG8_BAR; PG8_MMA(1, 0, At, B0); PG8_MMA(1, 1, At, B1); PG8_BAR; PG8_SCHED;
;             PG8_LDB(B0, 1, 0); PG8_LDB(B1, 1, 1); PG8_SCHED; PG8_LDA(At, 1, 0); PG8_STAGE(PG8_SA(0, 1), a2 + hstep, voffA);
;             PG8_WAIT_V(8); PG8_WAIT_L(0); PG8_BAR; PG8_MMA(0, 0, At, B0); PG8_MMA(0, 1, At, B1); PG8_BAR; PG8_SCHED;
	v_mfma_f32_16x16x32_bf16 v[60:63], v[128:131], v[196:199], 0
	v_mfma_f32_16x16x32_bf16 v[56:59], v[140:143], v[196:199], 0
	v_mfma_f32_16x16x32_bf16 v[44:47], v[128:131], v[204:207], 0
	v_mfma_f32_16x16x32_bf16 v[40:43], v[140:143], v[204:207], 0
	v_mfma_f32_16x16x32_bf16 v[28:31], v[128:131], v[212:215], 0
	v_mfma_f32_16x16x32_bf16 v[24:27], v[140:143], v[212:215], 0
	v_mfma_f32_16x16x32_bf16 v[12:15], v[128:131], v[220:223], 0
	v_mfma_f32_16x16x32_bf16 v[8:11], v[140:143], v[220:223], 0
	v_mfma_f32_16x16x32_bf16 v[60:63], v[132:135], v[200:203], v[60:63]
	v_mfma_f32_16x16x32_bf16 v[56:59], v[176:179], v[200:203], v[56:59]
	v_mfma_f32_16x16x32_bf16 v[44:47], v[132:135], v[208:211], v[44:47]
	v_mfma_f32_16x16x32_bf16 v[40:43], v[176:179], v[208:211], v[40:43]
	v_mfma_f32_16x16x32_bf16 v[28:31], v[132:135], v[216:219], v[28:31]
	v_mfma_f32_16x16x32_bf16 v[24:27], v[176:179], v[216:219], v[24:27]
	v_mfma_f32_16x16x32_bf16 v[12:15], v[132:135], v[224:227], v[12:15]
	v_mfma_f32_16x16x32_bf16 v[8:11], v[176:179], v[224:227], v[8:11]
	s_setprio 0
	s_setprio 1
	v_mfma_f32_16x16x32_bf16 v[52:55], v[180:183], v[196:199], 0
	v_mfma_f32_16x16x32_bf16 v[48:51], v[188:191], v[196:199], 0
	v_mfma_f32_16x16x32_bf16 v[36:39], v[180:183], v[204:207], 0
	v_mfma_f32_16x16x32_bf16 v[32:35], v[188:191], v[204:207], 0
	v_mfma_f32_16x16x32_bf16 v[20:23], v[180:183], v[212:215], 0
	v_mfma_f32_16x16x32_bf16 v[16:19], v[188:191], v[212:215], 0
	v_mfma_f32_16x16x32_bf16 v[4:7], v[180:183], v[220:223], 0
	v_mfma_f32_16x16x32_bf16 v[0:3], v[188:191], v[220:223], 0
	v_mfma_f32_16x16x32_bf16 v[52:55], v[184:187], v[200:203], v[52:55]
	v_mfma_f32_16x16x32_bf16 v[48:51], v[192:195], v[200:203], v[48:51]
	v_mfma_f32_16x16x32_bf16 v[36:39], v[184:187], v[208:211], v[36:39]
	v_mfma_f32_16x16x32_bf16 v[32:35], v[192:195], v[208:211], v[32:35]
	v_mfma_f32_16x16x32_bf16 v[20:23], v[184:187], v[216:219], v[20:23]
	v_mfma_f32_16x16x32_bf16 v[16:19], v[192:195], v[216:219], v[16:19]
	v_mfma_f32_16x16x32_bf16 v[4:7], v[184:187], v[224:227], v[4:7]
	v_mfma_f32_16x16x32_bf16 v[0:3], v[192:195], v[224:227], v[0:3]
	s_barrier
	s_setprio 0
	s_add_i32 s82, 0, 0x18000
	v_add_u32_e32 v144, s82, v146
	s_add_i32 s83, 0, 0x1c000
	ds_read_b128 v[128:131], v144
	ds_read_b128 v[132:135], v144 offset:1024
	ds_read_b128 v[140:143], v144 offset:2048
	ds_read_b128 v[176:179], v144 offset:3072
	v_add_u32_e32 v144, s83, v146
	ds_read_b128 v[180:183], v144
	ds_read_b128 v[184:187], v144 offset:1024
	ds_read_b128 v[188:191], v144 offset:2048
	ds_read_b128 v[192:195], v144 offset:3072
	s_add_u32 s34, s34, 0x40000
	s_addc_u32 s35, s35, 0
	s_mov_b32 m0, s38
	v_lshl_add_u64 v[238:239], s[34:35], 0, v[156:157]
	ds_read_b128 v[196:199], v151 offset:32768
	ds_read_b128 v[200:203], v151 offset:33792
	ds_read_b128 v[204:207], v151 offset:34816
	ds_read_b128 v[208:211], v151 offset:35840
	ds_read_b128 v[212:215], v151 offset:36864
	ds_read_b128 v[216:219], v151 offset:37888
	ds_read_b128 v[220:223], v151 offset:38912
	ds_read_b128 v[224:227], v151 offset:39936
	global_load_lds_dwordx4 v[238:239], off
	v_lshl_add_u64 v[238:239], s[34:35], 0, v[160:161]
	s_mov_b32 m0, s39
	s_nop 0
	global_load_lds_dwordx4 v[238:239], off
	s_waitcnt vmcnt(8)
	s_waitcnt lgkmcnt(0)
	s_setprio 1
	s_barrier
	v_mfma_f32_16x16x32_bf16 v[124:127], v[128:131], v[196:199], v[124:127]
	v_mfma_f32_16x16x32_bf16 v[120:123], v[140:143], v[196:199], v[120:123]
	v_mfma_f32_16x16x32_bf16 v[108:111], v[128:131], v[204:207], v[108:111]
	v_mfma_f32_16x16x32_bf16 v[104:107], v[140:143], v[204:207], v[104:107]
	v_mfma_f32_16x16x32_bf16 v[92:95], v[128:131], v[212:215], v[92:95]
	v_mfma_f32_16x16x32_bf16 v[88:91], v[140:143], v[212:215], v[88:91]
	v_mfma_f32_16x16x32_bf16 v[76:79], v[128:131], v[220:223], v[76:79]
	v_mfma_f32_16x16x32_bf16 v[72:75], v[140:143], v[220:223], v[72:75]
	v_mfma_f32_16x16x32_bf16 v[124:127], v[132:135], v[200:203], v[124:127]
	v_mfma_f32_16x16x32_bf16 v[120:123], v[176:179], v[200:203], v[120:123]
	v_mfma_f32_16x16x32_bf16 v[108:111], v[132:135], v[208:211], v[108:111]
	v_mfma_f32_16x16x32_bf16 v[104:107], v[176:179], v[208:211], v[104:107]
	v_mfma_f32_16x16x32_bf16 v[92:95], v[132:135], v[216:219], v[92:95]
	v_mfma_f32_16x16x32_bf16 v[88:91], v[176:179], v[216:219], v[88:91]
	v_mfma_f32_16x16x32_bf16 v[76:79], v[132:135], v[224:227], v[76:79]
	v_mfma_f32_16x16x32_bf16 v[72:75], v[176:179], v[224:227], v[72:75]
	s_setprio 0
	s_setprio 1
	v_mfma_f32_16x16x32_bf16 v[116:119], v[180:183], v[196:199], v[116:119]
	v_mfma_f32_16x16x32_bf16 v[112:115], v[188:191], v[196:199], v[112:115]
	v_mfma_f32_16x16x32_bf16 v[100:103], v[180:183], v[204:207], v[100:103]
	v_mfma_f32_16x16x32_bf16 v[96:99], v[188:191], v[204:207], v[96:99]
	v_mfma_f32_16x16x32_bf16 v[84:87], v[180:183], v[212:215], v[84:87]
	v_mfma_f32_16x16x32_bf16 v[80:83], v[188:191], v[212:215], v[80:83]
	v_mfma_f32_16x16x32_bf16 v[68:71], v[180:183], v[220:223], v[68:71]
	v_mfma_f32_16x16x32_bf16 v[64:67], v[188:191], v[220:223], v[64:67]
	v_mfma_f32_16x16x32_bf16 v[116:119], v[184:187], v[200:203], v[116:119]
	v_mfma_f32_16x16x32_bf16 v[112:115], v[192:195], v[200:203], v[112:115]
	v_mfma_f32_16x16x32_bf16 v[100:103], v[184:187], v[208:211], v[100:103]
	v_mfma_f32_16x16x32_bf16 v[96:99], v[192:195], v[208:211], v[96:99]
	v_mfma_f32_16x16x32_bf16 v[84:87], v[184:187], v[216:219], v[84:87]
	v_mfma_f32_16x16x32_bf16 v[80:83], v[192:195], v[216:219], v[80:83]
	v_mfma_f32_16x16x32_bf16 v[68:71], v[184:187], v[224:227], v[68:71]
	v_mfma_f32_16x16x32_bf16 v[64:67], v[192:195], v[224:227], v[64:67]
	s_barrier
; #define PG8_STAGE(bufoff, gbase, voff) do { _Pragma("unroll") for (int _i = 0; _i < 2; ++_i) \
;         __builtin_amdgcn_global_load_lds((const unsigned*)((const char*)(gbase) + (voff)[_i]), (PG8_LAS unsigned*)(lds + (bufoff) + ldsw + _i * 8192), 16, 0, 0); } while (0)
; #define PG8_LDA(dst, b, h) do { _Pragma("unroll") for (int m = 0; m < 4; ++m) _Pragma("unroll") for (int k = 0; k < 2; ++k) dst[m][k] = *(const PG8_LAS bf16x8*)(lds + PG8_SA(b, h) + aoff + m * 2048 + k * 1024); } while (0)
; #define PG8_MMA(ai, bj, At, Bt) do { __builtin_amdgcn_s_setprio(1); _Pragma("unroll") for (int m = 0; m < 4; ++m) _Pragma("unroll") for (int n = 0; n < 2; ++n) _Pragma("unroll") for (int k = 0; k < 2; ++k) \
;         acc[ai][bj][m][n] = __builtin_amdgcn_mfma_f32_16x16x32_bf16(Bt[n][k], At[m][k], acc[ai][bj][m][n], 0, 0, 0); __builtin_amdgcn_s_setprio(0); } while (0)
; #define PG8_WAIT_V(n) asm volatile("s_waitcnt vmcnt(" #n ")" ::: "memory")
; #define PG8_WAIT_L(n) asm volatile("s_waitcnt lgkmcnt(" #n ")" ::: "memory")
; #define PG8_BAR __builtin_amdgcn_s_barrier()
; #define PG8_SCHED __builtin_amdgcn_sched_barrier(0)
; template <class Epi, class Sched, bool ALIGN_EPI = false, bool SP2 = false>
; __device__ __forceinline__ void gemm_phase(PG8_LAS unsigned char* lds, const Gemm g, const Sched& S, const Epi& E) {
;     ...
;         for (int t = 0; t < nt; t += 2) {
;     ...
;             PG8_LDA(At, 1, 1); PG8_STAGE(PG8_SB(1, 0), b3, voffB); PG8_STAGE(PG8_SB(1, 1), b3 + hstep, voffB); PG8_STAGE(PG8_SA(1, 0), a3, voffA);
;             PG8_WAIT_V(8); PG8_WAIT_L(0); PG8_BAR; PG8_MMA(1, 0, At, B0); PG8_MMA(1, 1, At, B1); PG8_BAR; PG8_SCHED;
	s_setprio 0
	s_add_i32 s34, s82, s3
	v_lshl_add_u64 v[228:229], v[228:229], 0, s[6:7]
	s_mov_b32 m0, s34
	ds_read_b128 v[196:199], v151 offset:49152
	ds_read_b128 v[200:203], v151 offset:50176
	ds_read_b128 v[204:207], v151 offset:51200
	ds_read_b128 v[208:211], v151 offset:52224
	ds_read_b128 v[212:215], v151 offset:53248
	ds_read_b128 v[216:219], v151 offset:54272
	ds_read_b128 v[220:223], v151 offset:55296
	ds_read_b128 v[224:227], v151 offset:56320
	global_load_lds_dwordx4 v[228:229], off
	s_add_i32 m0, s34, 0x2000
	s_add_u32 s30, s30, 0x40080
	v_lshl_add_u64 v[228:229], v[248:249], 0, s[6:7]
	s_addc_u32 s31, s31, 0
	s_add_i32 s34, s83, s3
	global_load_lds_dwordx4 v[228:229], off
	v_lshl_add_u64 v[228:229], s[30:31], 0, v[158:159]
	s_mov_b32 m0, s34
	s_nop 0
	global_load_lds_dwordx4 v[228:229], off
	v_lshl_add_u64 v[228:229], s[30:31], 0, v[162:163]
	s_add_i32 m0, s34, 0x2000
	s_nop 0
	global_load_lds_dwordx4 v[228:229], off
	v_lshl_add_u64 v[228:229], v[250:251], 0, s[6:7]
	s_mov_b32 m0, s41
	s_nop 0
	global_load_lds_dwordx4 v[228:229], off
	v_lshl_add_u64 v[228:229], v[252:253], 0, s[6:7]
	s_mov_b32 m0, s42
	s_nop 0
	global_load_lds_dwordx4 v[228:229], off
	s_waitcnt vmcnt(8)
	s_waitcnt lgkmcnt(0)
	s_setprio 1
	s_barrier
	v_mfma_f32_16x16x32_bf16 v[60:63], v[128:131], v[196:199], v[60:63]
	v_mfma_f32_16x16x32_bf16 v[56:59], v[140:143], v[196:199], v[56:59]
	v_mfma_f32_16x16x32_bf16 v[44:47], v[128:131], v[204:207], v[44:47]
	v_mfma_f32_16x16x32_bf16 v[40:43], v[140:143], v[204:207], v[40:43]
	v_mfma_f32_16x16x32_bf16 v[28:31], v[128:131], v[212:215], v[28:31]
	v_mfma_f32_16x16x32_bf16 v[24:27], v[140:143], v[212:215], v[24:27]
	v_mfma_f32_16x16x32_bf16 v[12:15], v[128:131], v[220:223], v[12:15]
	v_mfma_f32_16x16x32_bf16 v[8:11], v[140:143], v[220:223], v[8:11]
	v_mfma_f32_16x16x32_bf16 v[60:63], v[132:135], v[200:203], v[60:63]
	v_mfma_f32_16x16x32_bf16 v[56:59], v[176:179], v[200:203], v[56:59]
	v_mfma_f32_16x16x32_bf16 v[44:47], v[132:135], v[208:211], v[44:47]
	v_mfma_f32_16x16x32_bf16 v[40:43], v[176:179], v[208:211], v[40:43]
	v_mfma_f32_16x16x32_bf16 v[28:31], v[132:135], v[216:219], v[28:31]
	v_mfma_f32_16x16x32_bf16 v[24:27], v[176:179], v[216:219], v[24:27]
	v_mfma_f32_16x16x32_bf16 v[12:15], v[132:135], v[224:227], v[12:15]
	v_mfma_f32_16x16x32_bf16 v[8:11], v[176:179], v[224:227], v[8:11]
	s_setprio 0
	s_setprio 1
	v_mfma_f32_16x16x32_bf16 v[52:55], v[180:183], v[196:199], v[52:55]
	v_mfma_f32_16x16x32_bf16 v[48:51], v[188:191], v[196:199], v[48:51]
	v_mfma_f32_16x16x32_bf16 v[36:39], v[180:183], v[204:207], v[36:39]
	v_mfma_f32_16x16x32_bf16 v[32:35], v[188:191], v[204:207], v[32:35]
	v_mfma_f32_16x16x32_bf16 v[20:23], v[180:183], v[212:215], v[20:23]
	v_mfma_f32_16x16x32_bf16 v[16:19], v[188:191], v[212:215], v[16:19]
	v_mfma_f32_16x16x32_bf16 v[4:7], v[180:183], v[220:223], v[4:7]
	v_mfma_f32_16x16x32_bf16 v[0:3], v[188:191], v[220:223], v[0:3]
	v_mfma_f32_16x16x32_bf16 v[52:55], v[184:187], v[200:203], v[52:55]
	v_mfma_f32_16x16x32_bf16 v[48:51], v[192:195], v[200:203], v[48:51]
	v_mfma_f32_16x16x32_bf16 v[36:39], v[184:187], v[208:211], v[36:39]
	v_mfma_f32_16x16x32_bf16 v[32:35], v[192:195], v[208:211], v[32:35]
	v_mfma_f32_16x16x32_bf16 v[20:23], v[184:187], v[216:219], v[20:23]
	v_mfma_f32_16x16x32_bf16 v[16:19], v[192:195], v[216:219], v[16:19]
	v_mfma_f32_16x16x32_bf16 v[4:7], v[184:187], v[224:227], v[4:7]
	v_mfma_f32_16x16x32_bf16 v[0:3], v[192:195], v[224:227], v[0:3]
	s_barrier
	s_setprio 0
	s_add_i32 s81, s81, 2
	s_add_u32 s0, s0, 0x100
	s_addc_u32 s1, s1, 0
	s_add_u32 s59, s59, 0x100
	s_addc_u32 s80, s80, 0
	s_cmp_gt_u32 s81, 13
	s_cbranch_scc1 .Lpeel_done_g2

; #define PG8_STAGE(bufoff, gbase, voff) do { _Pragma("unroll") for (int _i = 0; _i < 2; ++_i) \
;         __builtin_amdgcn_global_load_lds((const unsigned*)((const char*)(gbase) + (voff)[_i]), (PG8_LAS unsigned*)(lds + (bufoff) + ldsw + _i * 8192), 16, 0, 0); } while (0)
; #define PG8_LDA(dst, b, h) do { _Pragma("unroll") for (int m = 0; m < 4; ++m) _Pragma("unroll") for (int k = 0; k < 2; ++k) dst[m][k] = *(const PG8_LAS bf16x8*)(lds + PG8_SA(b, h) + aoff + m * 2048 + k * 1024); } while (0)
; #define PG8_LDB(dst, b, h) do { _Pragma("unroll") for (int n = 0; n < 2; ++n) _Pragma("unroll") for (int k = 0; k < 2; ++k) dst[n][k] = *(const PG8_LAS bf16x8*)(lds + PG8_SB(b, h) + boff + n * 2048 + k * 1024); } while (0)
; #define PG8_WAIT_V(n) asm volatile("s_waitcnt vmcnt(" #n ")" ::: "memory")
; #define PG8_WAIT_L(n) asm volatile("s_waitcnt lgkmcnt(" #n ")" ::: "memory")
; #define PG8_BAR __builtin_amdgcn_s_barrier()
; #define PG8_SCHED __builtin_amdgcn_sched_barrier(0)
; template <class Epi, class Sched, bool ALIGN_EPI = false, bool SP2 = false>
; __device__ __forceinline__ void gemm_phase(PG8_LAS unsigned char* lds, const Gemm g, const Sched& S, const Epi& E) {
;     ...
;         const bool has_next = S.next(ui + 1, nxt);
;         const char* nA = has_next ? (const char*)g.A + (size_t)nxt.pm * tstep : cA; const char* nB = has_next ? (const char*)g.Bt + (size_t)nxt.pn * tstep : cB;
;         for (int t = 0; t < nt; t += 2) {
;             const bool last = (t == nt - 2);
;             const char* a1 = cA + (size_t)(t + 1) * kstep;
;             const char* a2 = last ? nA : cA + (size_t)(t + 2) * kstep; const char* b2 = last ? nB : cB + (size_t)(t + 2) * kstep;
;             const char* a3 = a2 + kstep; const char* b3 = b2 + kstep;
;             if (last && has_next) S.a_ready(nxt);
;             if constexpr (SP2) {
;             PG8_LDB(B0, 0, 0); PG8_LDB(B1, 0, 1); PG8_SCHED; PG8_LDA(At, 0, 0); PG8_STAGE(PG8_SA(1, 1), a1 + hstep, voffA);
;             PG8_WAIT_V(8); PG8_WAIT_L(0); PG8_BAR; PG8_MMA(0, 0, At, B0); PG8_MMA(0, 1, At, B1); PG8_BAR; PG8_SCHED;
;             PG8_LDA(At, 0, 1); PG8_STAGE(PG8_SB(0, 0), b2, voffB); PG8_STAGE(PG8_SB(0, 1), b2 + hstep, voffB); PG8_STAGE(PG8_SA(0, 0), a2, voffA);
;             PG8_WAIT_V(8); PG8_WAIT_L(0); PG8_BAR; PG8_MMA(1, 0, At, B0); PG8_MMA(1, 1, At, B1); PG8_BAR; PG8_SCHED;
.LBB0_1229:
	s_ashr_i32 s19, s18, 31
	s_lshl_b64 s[20:21], s[18:19], 19
	s_add_u32 s20, s48, s20
	s_addc_u32 s21, s49, s21
	s_and_b64 s[22:23], s[10:11], exec
	s_cselect_b32 s19, s21, s27
	s_cselect_b32 s25, s20, s26
	s_ashr_i32 s17, s16, 31
	s_lshl_b64 s[22:23], s[16:17], 19
	s_add_u32 s22, s2, s22
	s_addc_u32 s23, s3, s23
	s_and_b64 s[30:31], s[10:11], exec
	s_cselect_b32 s17, s23, s29
	s_cselect_b32 s47, s22, s28
	s_add_u32 s26, s26, 0x40080
	s_addc_u32 s27, s27, 0
	s_add_u32 s50, s28, 0x100
	s_addc_u32 s51, s29, 0
	s_mov_b32 s52, -2
	s_waitcnt lgkmcnt(0)
	ds_read_b128 v[128:131], v200
	ds_read_b128 v[132:135], v200 offset:1024
	ds_read_b128 v[136:139], v200 offset:2048
	ds_read_b128 v[140:143], v200 offset:3072
	ds_read_b128 v[144:147], v201
	ds_read_b128 v[148:151], v201 offset:1024
	ds_read_b128 v[182:185], v201 offset:2048
	ds_read_b128 v[186:189], v201 offset:3072
	s_add_u32 s28, s26, 0xfffc0080
	s_addc_u32 s29, s27, -1
	s_cmp_eq_u32 s52, 12
	s_cselect_b32 s31, s19, s29
	s_cselect_b32 s30, s25, s28
	s_cselect_b32 s29, s17, s51
	s_cselect_b32 s28, s47, s50
	v_lshl_add_u64 v[198:199], s[26:27], 0, v[174:175]
	s_add_i32 m0, s34, 0xc000
	ds_read_b128 v[190:193], v202
	ds_read_b128 v[194:197], v202 offset:1024
	ds_read_b128 v[204:207], v202 offset:2048
	ds_read_b128 v[208:211], v202 offset:3072
	ds_read_b128 v[212:215], v202 offset:4096
	ds_read_b128 v[216:219], v202 offset:5120
	ds_read_b128 v[220:223], v202 offset:6144
	ds_read_b128 v[224:227], v202 offset:7168
	global_load_lds_dwordx4 v[198:199], off
	v_lshl_add_u64 v[198:199], s[26:27], 0, v[176:177]
	s_add_i32 m0, s34, 0xe000
	s_nop 0
	global_load_lds_dwordx4 v[198:199], off
	s_waitcnt vmcnt(8)
	s_waitcnt lgkmcnt(0)
	s_setprio 1
	s_barrier
	v_mfma_f32_16x16x32_bf16 v[124:127], v[128:131], v[190:193], 0
	v_mfma_f32_16x16x32_bf16 v[120:123], v[136:139], v[190:193], 0
	v_mfma_f32_16x16x32_bf16 v[108:111], v[128:131], v[204:207], 0
	v_mfma_f32_16x16x32_bf16 v[104:107], v[136:139], v[204:207], 0
	v_mfma_f32_16x16x32_bf16 v[92:95], v[128:131], v[212:215], 0
	v_mfma_f32_16x16x32_bf16 v[88:91], v[136:139], v[212:215], 0
	v_mfma_f32_16x16x32_bf16 v[76:79], v[128:131], v[220:223], 0
	v_mfma_f32_16x16x32_bf16 v[72:75], v[136:139], v[220:223], 0
	v_mfma_f32_16x16x32_bf16 v[124:127], v[132:135], v[194:197], v[124:127]
	v_mfma_f32_16x16x32_bf16 v[120:123], v[140:143], v[194:197], v[120:123]
	v_mfma_f32_16x16x32_bf16 v[108:111], v[132:135], v[208:211], v[108:111]
	v_mfma_f32_16x16x32_bf16 v[104:107], v[140:143], v[208:211], v[104:107]
	v_mfma_f32_16x16x32_bf16 v[92:95], v[132:135], v[216:219], v[92:95]
	v_mfma_f32_16x16x32_bf16 v[88:91], v[140:143], v[216:219], v[88:91]
	v_mfma_f32_16x16x32_bf16 v[76:79], v[132:135], v[224:227], v[76:79]
	v_mfma_f32_16x16x32_bf16 v[72:75], v[140:143], v[224:227], v[72:75]
	s_setprio 0
	s_setprio 1
	v_mfma_f32_16x16x32_bf16 v[116:119], v[144:147], v[190:193], 0
	v_mfma_f32_16x16x32_bf16 v[112:115], v[182:185], v[190:193], 0
	v_mfma_f32_16x16x32_bf16 v[100:103], v[144:147], v[204:207], 0
	v_mfma_f32_16x16x32_bf16 v[96:99], v[182:185], v[204:207], 0
	v_mfma_f32_16x16x32_bf16 v[84:87], v[144:147], v[212:215], 0
	v_mfma_f32_16x16x32_bf16 v[80:83], v[182:185], v[212:215], 0
	v_mfma_f32_16x16x32_bf16 v[68:71], v[144:147], v[220:223], 0
	v_mfma_f32_16x16x32_bf16 v[64:67], v[182:185], v[220:223], 0
	v_mfma_f32_16x16x32_bf16 v[116:119], v[148:151], v[194:197], v[116:119]
	v_mfma_f32_16x16x32_bf16 v[112:115], v[186:189], v[194:197], v[112:115]
	v_mfma_f32_16x16x32_bf16 v[100:103], v[148:151], v[208:211], v[100:103]
	v_mfma_f32_16x16x32_bf16 v[96:99], v[186:189], v[208:211], v[96:99]
	v_mfma_f32_16x16x32_bf16 v[84:87], v[148:151], v[216:219], v[84:87]
	v_mfma_f32_16x16x32_bf16 v[80:83], v[186:189], v[216:219], v[80:83]
	v_mfma_f32_16x16x32_bf16 v[68:71], v[148:151], v[224:227], v[68:71]
	v_mfma_f32_16x16x32_bf16 v[64:67], v[186:189], v[224:227], v[64:67]
	s_barrier
	s_setprio 0
	s_add_i32 s53, s44, s33
	v_lshl_add_u64 v[198:199], s[28:29], 0, v[158:159]
	s_mov_b32 m0, s53
	ds_read_b128 v[190:193], v202 offset:16384
	ds_read_b128 v[194:197], v202 offset:17408
	ds_read_b128 v[204:207], v202 offset:18432
	ds_read_b128 v[208:211], v202 offset:19456
	ds_read_b128 v[212:215], v202 offset:20480
	ds_read_b128 v[216:219], v202 offset:21504
	ds_read_b128 v[220:223], v202 offset:22528
	ds_read_b128 v[224:227], v202 offset:23552
	global_load_lds_dwordx4 v[198:199], off
	s_add_i32 m0, s53, 0x2000
	s_add_u32 s54, s28, 0x40000
	v_lshl_add_u64 v[228:229], s[28:29], 0, v[162:163]
	s_addc_u32 s55, s29, 0
	s_add_i32 s53, s45, s33
	global_load_lds_dwordx4 v[228:229], off
	v_lshl_add_u64 v[238:239], s[54:55], 0, v[158:159]
	s_mov_b32 m0, s53
	v_lshl_add_u64 v[246:247], s[30:31], 0, v[160:161]
	global_load_lds_dwordx4 v[238:239], off
	v_lshl_add_u64 v[238:239], s[54:55], 0, v[162:163]
	s_add_i32 m0, s53, 0x2000
	s_nop 0
	global_load_lds_dwordx4 v[238:239], off
	v_lshl_add_u64 v[238:239], s[30:31], 0, v[156:157]
	s_mov_b32 m0, s34
	s_nop 0
	global_load_lds_dwordx4 v[238:239], off
	s_mov_b32 m0, s35
	s_nop 0
	global_load_lds_dwordx4 v[246:247], off
	s_waitcnt vmcnt(8)
	s_waitcnt lgkmcnt(0)
	s_setprio 1
	s_barrier
; #define PG8_STAGE(bufoff, gbase, voff) do { _Pragma("unroll") for (int _i = 0; _i < 2; ++_i) \
;         __builtin_amdgcn_global_load_lds((const unsigned*)((const char*)(gbase) + (voff)[_i]), (PG8_LAS unsigned*)(lds + (bufoff) + ldsw + _i * 8192), 16, 0, 0); } while (0)
; #define PG8_LDA(dst, b, h) do { _Pragma("unroll") for (int m = 0; m < 4; ++m) _Pragma("unroll") for (int k = 0; k < 2; ++k) dst[m][k] = *(const PG8_LAS bf16x8*)(lds + PG8_SA(b, h) + aoff + m * 2048 + k * 1024); } while (0)
; #define PG8_LDB(dst, b, h) do { _Pragma("unroll") for (int n = 0; n < 2; ++n) _Pragma("unroll") for (int k = 0; k < 2; ++k) dst[n][k] = *(const PG8_LAS bf16x8*)(lds + PG8_SB(b, h) + boff + n * 2048 + k * 1024); } while (0)
; #define PG8_MMA(ai, bj, At, Bt) do { __builtin_amdgcn_s_setprio(1); _Pragma("unroll") for (int m = 0; m < 4; ++m) _Pragma("unroll") for (int n = 0; n < 2; ++n) _Pragma("unroll") for (int k = 0; k < 2; ++k) \
;         acc[ai][bj][m][n] = __builtin_amdgcn_mfma_f32_16x16x32_bf16(Bt[n][k], At[m][k], acc[ai][bj][m][n], 0, 0, 0); __builtin_amdgcn_s_setprio(0); } while (0)
; #define PG8_WAIT_V(n) asm volatile("s_waitcnt vmcnt(" #n ")" ::: "memory")
; #define PG8_WAIT_L(n) asm volatile("s_waitcnt lgkmcnt(" #n ")" ::: "memory")
; #define PG8_BAR __builtin_amdgcn_s_barrier()
; #define PG8_SCHED __builtin_amdgcn_sched_barrier(0)
; template <class Epi, class Sched, bool ALIGN_EPI = false, bool SP2 = false>
; __device__ __forceinline__ void gemm_phase(PG8_LAS unsigned char* lds, const Gemm g, const Sched& S, const Epi& E) {
;     ...
;             PG8_WAIT_V(8); PG8_WAIT_L(0); PG8_BAR; PG8_MMA(1, 0, At, B0); PG8_MMA(1, 1, At, B1); PG8_BAR; PG8_SCHED;
;             PG8_LDB(B0, 1, 0); PG8_LDB(B1, 1, 1); PG8_SCHED; PG8_LDA(At, 1, 0); PG8_STAGE(PG8_SA(0, 1), a2 + hstep, voffA);
;             PG8_WAIT_V(8); PG8_WAIT_L(0); PG8_BAR; PG8_MMA(0, 0, At, B0); PG8_MMA(0, 1, At, B1); PG8_BAR; PG8_SCHED;
	v_mfma_f32_16x16x32_bf16 v[60:63], v[128:131], v[190:193], 0
	v_mfma_f32_16x16x32_bf16 v[56:59], v[136:139], v[190:193], 0
	v_mfma_f32_16x16x32_bf16 v[44:47], v[128:131], v[204:207], 0
	v_mfma_f32_16x16x32_bf16 v[40:43], v[136:139], v[204:207], 0
	v_mfma_f32_16x16x32_bf16 v[28:31], v[128:131], v[212:215], 0
	v_mfma_f32_16x16x32_bf16 v[24:27], v[136:139], v[212:215], 0
	v_mfma_f32_16x16x32_bf16 v[12:15], v[128:131], v[220:223], 0
	v_mfma_f32_16x16x32_bf16 v[8:11], v[136:139], v[220:223], 0
	v_mfma_f32_16x16x32_bf16 v[60:63], v[132:135], v[194:197], v[60:63]
	v_mfma_f32_16x16x32_bf16 v[56:59], v[140:143], v[194:197], v[56:59]
	v_mfma_f32_16x16x32_bf16 v[44:47], v[132:135], v[208:211], v[44:47]
	v_mfma_f32_16x16x32_bf16 v[40:43], v[140:143], v[208:211], v[40:43]
	v_mfma_f32_16x16x32_bf16 v[28:31], v[132:135], v[216:219], v[28:31]
	v_mfma_f32_16x16x32_bf16 v[24:27], v[140:143], v[216:219], v[24:27]
	v_mfma_f32_16x16x32_bf16 v[12:15], v[132:135], v[224:227], v[12:15]
	v_mfma_f32_16x16x32_bf16 v[8:11], v[140:143], v[224:227], v[8:11]
	s_setprio 0
	s_setprio 1
	v_mfma_f32_16x16x32_bf16 v[52:55], v[144:147], v[190:193], 0
	v_mfma_f32_16x16x32_bf16 v[48:51], v[182:185], v[190:193], 0
	v_mfma_f32_16x16x32_bf16 v[36:39], v[144:147], v[204:207], 0
	v_mfma_f32_16x16x32_bf16 v[32:35], v[182:185], v[204:207], 0
	v_mfma_f32_16x16x32_bf16 v[20:23], v[144:147], v[212:215], 0
	v_mfma_f32_16x16x32_bf16 v[16:19], v[182:185], v[212:215], 0
	v_mfma_f32_16x16x32_bf16 v[4:7], v[144:147], v[220:223], 0
	v_mfma_f32_16x16x32_bf16 v[0:3], v[182:185], v[220:223], 0
	v_mfma_f32_16x16x32_bf16 v[52:55], v[148:151], v[194:197], v[52:55]
	v_mfma_f32_16x16x32_bf16 v[48:51], v[186:189], v[194:197], v[48:51]
	v_mfma_f32_16x16x32_bf16 v[36:39], v[148:151], v[208:211], v[36:39]
	v_mfma_f32_16x16x32_bf16 v[32:35], v[186:189], v[208:211], v[32:35]
	v_mfma_f32_16x16x32_bf16 v[20:23], v[148:151], v[216:219], v[20:23]
	v_mfma_f32_16x16x32_bf16 v[16:19], v[186:189], v[216:219], v[16:19]
	v_mfma_f32_16x16x32_bf16 v[4:7], v[148:151], v[224:227], v[4:7]
	v_mfma_f32_16x16x32_bf16 v[0:3], v[186:189], v[224:227], v[0:3]
	s_barrier
	s_setprio 0
	s_add_i32 s53, 0, 0x18000
	s_add_i32 s54, 0, 0x1c000
	v_add_u32_e32 v140, s53, v169
	v_add_u32_e32 v186, s54, v169
	ds_read_b128 v[128:131], v140
	ds_read_b128 v[132:135], v140 offset:1024
	ds_read_b128 v[136:139], v140 offset:2048
	ds_read_b128 v[140:143], v140 offset:3072
	ds_read_b128 v[144:147], v186
	ds_read_b128 v[148:151], v186 offset:1024
	ds_read_b128 v[182:185], v186 offset:2048
	ds_read_b128 v[186:189], v186 offset:3072
	s_add_u32 s30, s30, 0x40000
	s_addc_u32 s31, s31, 0
	s_mov_b32 m0, s36
	v_lshl_add_u64 v[248:249], s[30:31], 0, v[156:157]
	ds_read_b128 v[190:193], v202 offset:32768
	ds_read_b128 v[194:197], v202 offset:33792
	ds_read_b128 v[204:207], v202 offset:34816
	ds_read_b128 v[208:211], v202 offset:35840
	ds_read_b128 v[212:215], v202 offset:36864
	ds_read_b128 v[216:219], v202 offset:37888
	ds_read_b128 v[220:223], v202 offset:38912
	ds_read_b128 v[224:227], v202 offset:39936
	global_load_lds_dwordx4 v[248:249], off
	v_lshl_add_u64 v[248:249], s[30:31], 0, v[160:161]
	s_mov_b32 m0, s37
	s_nop 0
	global_load_lds_dwordx4 v[248:249], off
	s_waitcnt vmcnt(8)
	s_waitcnt lgkmcnt(0)
	s_setprio 1
	s_barrier
	v_mfma_f32_16x16x32_bf16 v[124:127], v[128:131], v[190:193], v[124:127]
	v_mfma_f32_16x16x32_bf16 v[120:123], v[136:139], v[190:193], v[120:123]
	v_mfma_f32_16x16x32_bf16 v[108:111], v[128:131], v[204:207], v[108:111]
	v_mfma_f32_16x16x32_bf16 v[104:107], v[136:139], v[204:207], v[104:107]
	v_mfma_f32_16x16x32_bf16 v[92:95], v[128:131], v[212:215], v[92:95]
	v_mfma_f32_16x16x32_bf16 v[88:91], v[136:139], v[212:215], v[88:91]
	v_mfma_f32_16x16x32_bf16 v[76:79], v[128:131], v[220:223], v[76:79]
	v_mfma_f32_16x16x32_bf16 v[72:75], v[136:139], v[220:223], v[72:75]
	v_mfma_f32_16x16x32_bf16 v[124:127], v[132:135], v[194:197], v[124:127]
	v_mfma_f32_16x16x32_bf16 v[120:123], v[140:143], v[194:197], v[120:123]
	v_mfma_f32_16x16x32_bf16 v[108:111], v[132:135], v[208:211], v[108:111]
	v_mfma_f32_16x16x32_bf16 v[104:107], v[140:143], v[208:211], v[104:107]
	v_mfma_f32_16x16x32_bf16 v[92:95], v[132:135], v[216:219], v[92:95]
	v_mfma_f32_16x16x32_bf16 v[88:91], v[140:143], v[216:219], v[88:91]
	v_mfma_f32_16x16x32_bf16 v[76:79], v[132:135], v[224:227], v[76:79]
	v_mfma_f32_16x16x32_bf16 v[72:75], v[140:143], v[224:227], v[72:75]
	s_setprio 0
	s_setprio 1
	v_mfma_f32_16x16x32_bf16 v[116:119], v[144:147], v[190:193], v[116:119]
	v_mfma_f32_16x16x32_bf16 v[112:115], v[182:185], v[190:193], v[112:115]
	v_mfma_f32_16x16x32_bf16 v[100:103], v[144:147], v[204:207], v[100:103]
	v_mfma_f32_16x16x32_bf16 v[96:99], v[182:185], v[204:207], v[96:99]
	v_mfma_f32_16x16x32_bf16 v[84:87], v[144:147], v[212:215], v[84:87]
	v_mfma_f32_16x16x32_bf16 v[80:83], v[182:185], v[212:215], v[80:83]
	v_mfma_f32_16x16x32_bf16 v[68:71], v[144:147], v[220:223], v[68:71]
	v_mfma_f32_16x16x32_bf16 v[64:67], v[182:185], v[220:223], v[64:67]
	v_mfma_f32_16x16x32_bf16 v[116:119], v[148:151], v[194:197], v[116:119]
	v_mfma_f32_16x16x32_bf16 v[112:115], v[186:189], v[194:197], v[112:115]
	v_mfma_f32_16x16x32_bf16 v[100:103], v[148:151], v[208:211], v[100:103]
	v_mfma_f32_16x16x32_bf16 v[96:99], v[186:189], v[208:211], v[96:99]
	v_mfma_f32_16x16x32_bf16 v[84:87], v[148:151], v[216:219], v[84:87]
	v_mfma_f32_16x16x32_bf16 v[80:83], v[186:189], v[216:219], v[80:83]
	v_mfma_f32_16x16x32_bf16 v[68:71], v[148:151], v[224:227], v[68:71]
	v_mfma_f32_16x16x32_bf16 v[64:67], v[186:189], v[224:227], v[64:67]
	s_barrier
; #define PG8_STAGE(bufoff, gbase, voff) do { _Pragma("unroll") for (int _i = 0; _i < 2; ++_i) \
;         __builtin_amdgcn_global_load_lds((const unsigned*)((const char*)(gbase) + (voff)[_i]), (PG8_LAS unsigned*)(lds + (bufoff) + ldsw + _i * 8192), 16, 0, 0); } while (0)
; #define PG8_LDA(dst, b, h) do { _Pragma("unroll") for (int m = 0; m < 4; ++m) _Pragma("unroll") for (int k = 0; k < 2; ++k) dst[m][k] = *(const PG8_LAS bf16x8*)(lds + PG8_SA(b, h) + aoff + m * 2048 + k * 1024); } while (0)
; #define PG8_MMA(ai, bj, At, Bt) do { __builtin_amdgcn_s_setprio(1); _Pragma("unroll") for (int m = 0; m < 4; ++m) _Pragma("unroll") for (int n = 0; n < 2; ++n) _Pragma("unroll") for (int k = 0; k < 2; ++k) \
;         acc[ai][bj][m][n] = __builtin_amdgcn_mfma_f32_16x16x32_bf16(Bt[n][k], At[m][k], acc[ai][bj][m][n], 0, 0, 0); __builtin_amdgcn_s_setprio(0); } while (0)
; #define PG8_WAIT_V(n) asm volatile("s_waitcnt vmcnt(" #n ")" ::: "memory")
; #define PG8_WAIT_L(n) asm volatile("s_waitcnt lgkmcnt(" #n ")" ::: "memory")
; #define PG8_BAR __builtin_amdgcn_s_barrier()
; #define PG8_SCHED __builtin_amdgcn_sched_barrier(0)
; template <class Epi, class Sched, bool ALIGN_EPI = false, bool SP2 = false>
; __device__ __forceinline__ void gemm_phase(PG8_LAS unsigned char* lds, const Gemm g, const Sched& S, const Epi& E) {
;     ...
;         for (int t = 0; t < nt; t += 2) {
;     ...
;             PG8_LDA(At, 1, 1); PG8_STAGE(PG8_SB(1, 0), b3, voffB); PG8_STAGE(PG8_SB(1, 1), b3 + hstep, voffB); PG8_STAGE(PG8_SA(1, 0), a3, voffA);
;             PG8_WAIT_V(8); PG8_WAIT_L(0); PG8_BAR; PG8_MMA(1, 0, At, B0); PG8_MMA(1, 1, At, B1); PG8_BAR; PG8_SCHED;
	s_setprio 0
	s_add_i32 s30, s53, s33
	v_lshl_add_u64 v[198:199], v[198:199], 0, s[6:7]
	s_mov_b32 m0, s30
	ds_read_b128 v[190:193], v202 offset:49152
	ds_read_b128 v[194:197], v202 offset:50176
	ds_read_b128 v[204:207], v202 offset:51200
	ds_read_b128 v[208:211], v202 offset:52224
	ds_read_b128 v[212:215], v202 offset:53248
	ds_read_b128 v[216:219], v202 offset:54272
	ds_read_b128 v[220:223], v202 offset:55296
	ds_read_b128 v[224:227], v202 offset:56320
	global_load_lds_dwordx4 v[198:199], off
	s_add_i32 m0, s30, 0x2000
	s_add_u32 s28, s28, 0x40080
	v_lshl_add_u64 v[198:199], v[228:229], 0, s[6:7]
	s_addc_u32 s29, s29, 0
	s_add_i32 s30, s54, s33
	global_load_lds_dwordx4 v[198:199], off
	v_lshl_add_u64 v[198:199], s[28:29], 0, v[158:159]
	s_mov_b32 m0, s30
	s_nop 0
	global_load_lds_dwordx4 v[198:199], off
	v_lshl_add_u64 v[198:199], s[28:29], 0, v[162:163]
	s_add_i32 m0, s30, 0x2000
	s_nop 0
	global_load_lds_dwordx4 v[198:199], off
	v_lshl_add_u64 v[198:199], v[238:239], 0, s[6:7]
	s_mov_b32 m0, s39
	s_nop 0
	global_load_lds_dwordx4 v[198:199], off
	v_lshl_add_u64 v[198:199], v[246:247], 0, s[6:7]
	s_mov_b32 m0, s40
	s_nop 0
	global_load_lds_dwordx4 v[198:199], off
	s_waitcnt vmcnt(8)
	s_waitcnt lgkmcnt(0)
	s_setprio 1
	s_barrier
	v_mfma_f32_16x16x32_bf16 v[60:63], v[128:131], v[190:193], v[60:63]
	v_mfma_f32_16x16x32_bf16 v[56:59], v[136:139], v[190:193], v[56:59]
	v_mfma_f32_16x16x32_bf16 v[44:47], v[128:131], v[204:207], v[44:47]
	v_mfma_f32_16x16x32_bf16 v[40:43], v[136:139], v[204:207], v[40:43]
	v_mfma_f32_16x16x32_bf16 v[28:31], v[128:131], v[212:215], v[28:31]
	v_mfma_f32_16x16x32_bf16 v[24:27], v[136:139], v[212:215], v[24:27]
	v_mfma_f32_16x16x32_bf16 v[12:15], v[128:131], v[220:223], v[12:15]
	v_mfma_f32_16x16x32_bf16 v[8:11], v[136:139], v[220:223], v[8:11]
	v_mfma_f32_16x16x32_bf16 v[60:63], v[132:135], v[194:197], v[60:63]
	v_mfma_f32_16x16x32_bf16 v[56:59], v[140:143], v[194:197], v[56:59]
	v_mfma_f32_16x16x32_bf16 v[44:47], v[132:135], v[208:211], v[44:47]
	v_mfma_f32_16x16x32_bf16 v[40:43], v[140:143], v[208:211], v[40:43]
	v_mfma_f32_16x16x32_bf16 v[28:31], v[132:135], v[216:219], v[28:31]
	v_mfma_f32_16x16x32_bf16 v[24:27], v[140:143], v[216:219], v[24:27]
	v_mfma_f32_16x16x32_bf16 v[12:15], v[132:135], v[224:227], v[12:15]
	v_mfma_f32_16x16x32_bf16 v[8:11], v[140:143], v[224:227], v[8:11]
	s_setprio 0
	s_setprio 1
	v_mfma_f32_16x16x32_bf16 v[52:55], v[144:147], v[190:193], v[52:55]
	v_mfma_f32_16x16x32_bf16 v[48:51], v[182:185], v[190:193], v[48:51]
	v_mfma_f32_16x16x32_bf16 v[36:39], v[144:147], v[204:207], v[36:39]
	v_mfma_f32_16x16x32_bf16 v[32:35], v[182:185], v[204:207], v[32:35]
	v_mfma_f32_16x16x32_bf16 v[20:23], v[144:147], v[212:215], v[20:23]
	v_mfma_f32_16x16x32_bf16 v[16:19], v[182:185], v[212:215], v[16:19]
	v_mfma_f32_16x16x32_bf16 v[4:7], v[144:147], v[220:223], v[4:7]
	v_mfma_f32_16x16x32_bf16 v[0:3], v[182:185], v[220:223], v[0:3]
	v_mfma_f32_16x16x32_bf16 v[52:55], v[148:151], v[194:197], v[52:55]
	v_mfma_f32_16x16x32_bf16 v[48:51], v[186:189], v[194:197], v[48:51]
	v_mfma_f32_16x16x32_bf16 v[36:39], v[148:151], v[208:211], v[36:39]
	v_mfma_f32_16x16x32_bf16 v[32:35], v[186:189], v[208:211], v[32:35]
	v_mfma_f32_16x16x32_bf16 v[20:23], v[148:151], v[216:219], v[20:23]
	v_mfma_f32_16x16x32_bf16 v[16:19], v[186:189], v[216:219], v[16:19]
	v_mfma_f32_16x16x32_bf16 v[4:7], v[148:151], v[224:227], v[4:7]
	v_mfma_f32_16x16x32_bf16 v[0:3], v[186:189], v[224:227], v[0:3]
	s_barrier
	s_setprio 0
	s_add_i32 s52, s52, 2
	s_add_u32 s26, s26, 0x100
	s_addc_u32 s27, s27, 0
	s_add_u32 s50, s50, 0x100
	s_addc_u32 s51, s51, 0
	s_cmp_gt_u32 s52, 13
	s_cbranch_scc1 .Lpeel_done_g3

; #define PG8_BAR __builtin_amdgcn_s_barrier()
; template <class Epi, class Sched, bool ALIGN_EPI = false, bool SP2 = false>
; __device__ __forceinline__ void gemm_phase(PG8_LAS unsigned char* lds, const Gemm g, const Sched& S, const Epi& E) {
;     ...
;         if constexpr (ALIGN_EPI) { if (wr == 0) PG8_BAR; }
;         if constexpr (!Epi::AFTER_DRAIN) { E(acc, cur, wr, wc, fr, fq); S.done(cur); }
.Lpeel_done_g3:
	s_and_b64 vcc, exec, s[14:15]
	s_cbranch_vccz .LBB0_1233
	s_barrier

; #define PG8_STAGE(bufoff, gbase, voff) do { _Pragma("unroll") for (int _i = 0; _i < 2; ++_i) \
;         __builtin_amdgcn_global_load_lds((const unsigned*)((const char*)(gbase) + (voff)[_i]), (PG8_LAS unsigned*)(lds + (bufoff) + ldsw + _i * 8192), 16, 0, 0); } while (0)
; #define PG8_LDA(dst, b, h) do { _Pragma("unroll") for (int m = 0; m < 4; ++m) _Pragma("unroll") for (int k = 0; k < 2; ++k) dst[m][k] = *(const PG8_LAS bf16x8*)(lds + PG8_SA(b, h) + aoff + m * 2048 + k * 1024); } while (0)
; #define PG8_LDB(dst, b, h) do { _Pragma("unroll") for (int n = 0; n < 2; ++n) _Pragma("unroll") for (int k = 0; k < 2; ++k) dst[n][k] = *(const PG8_LAS bf16x8*)(lds + PG8_SB(b, h) + boff + n * 2048 + k * 1024); } while (0)
; #define PG8_WAIT_V(n) asm volatile("s_waitcnt vmcnt(" #n ")" ::: "memory")
; #define PG8_WAIT_L(n) asm volatile("s_waitcnt lgkmcnt(" #n ")" ::: "memory")
; #define PG8_BAR __builtin_amdgcn_s_barrier()
; #define PG8_SCHED __builtin_amdgcn_sched_barrier(0)
; template <class Epi, class Sched, bool ALIGN_EPI = false, bool SP2 = false>
; __device__ __forceinline__ void gemm_phase(PG8_LAS unsigned char* lds, const Gemm g, const Sched& S, const Epi& E) {
;     ...
;         const bool has_next = S.next(ui + 1, nxt);
;         const char* nA = has_next ? (const char*)g.A + (size_t)nxt.pm * tstep : cA; const char* nB = has_next ? (const char*)g.Bt + (size_t)nxt.pn * tstep : cB;
;         for (int t = 0; t < nt; t += 2) {
;             const bool last = (t == nt - 2);
;             const char* a1 = cA + (size_t)(t + 1) * kstep;
;             const char* a2 = last ? nA : cA + (size_t)(t + 2) * kstep; const char* b2 = last ? nB : cB + (size_t)(t + 2) * kstep;
;             const char* a3 = a2 + kstep; const char* b3 = b2 + kstep;
;             if (last && has_next) S.a_ready(nxt);
;             if constexpr (SP2) {
;             PG8_LDB(B0, 0, 0); PG8_LDB(B1, 0, 1); PG8_SCHED; PG8_LDA(At, 0, 0); PG8_STAGE(PG8_SA(1, 1), a1 + hstep, voffA);
;             PG8_WAIT_V(8); PG8_WAIT_L(0); PG8_BAR; PG8_MMA(0, 0, At, B0); PG8_MMA(0, 1, At, B1); PG8_BAR; PG8_SCHED;
;             PG8_LDA(At, 0, 1); PG8_STAGE(PG8_SB(0, 0), b2, voffB); PG8_STAGE(PG8_SB(0, 1), b2 + hstep, voffB); PG8_STAGE(PG8_SA(0, 0), a2, voffA);
;             PG8_WAIT_V(8); PG8_WAIT_L(0); PG8_BAR; PG8_MMA(1, 0, At, B0); PG8_MMA(1, 1, At, B1); PG8_BAR; PG8_SCHED;
.LBB0_1321:
	s_ashr_i32 s19, s18, 31
	s_lshl_b64 s[20:21], s[18:19], 19
	s_add_u32 s20, s76, s20
	s_addc_u32 s21, s77, s21
	s_and_b64 s[22:23], s[8:9], exec
	s_cselect_b32 s1, s21, s25
	s_cselect_b32 s11, s20, s24
	s_ashr_i32 s17, s16, 31
	s_lshl_b64 s[22:23], s[16:17], 19
	s_add_u32 s22, s30, s22
	s_addc_u32 s23, s31, s23
	s_and_b64 s[28:29], s[8:9], exec
	s_cselect_b32 s17, s23, s27
	s_cselect_b32 s19, s22, s26
	s_add_u32 s24, s24, 0x40080
	s_addc_u32 s25, s25, 0
	s_add_u32 s48, s26, 0x100
	s_addc_u32 s49, s27, 0
	s_mov_b32 s50, -2
	ds_read_b128 v[136:139], v144
	ds_read_b128 v[174:177], v144 offset:1024
	ds_read_b128 v[178:181], v144 offset:2048
	ds_read_b128 v[182:185], v144 offset:3072
	ds_read_b128 v[186:189], v145
	ds_read_b128 v[190:193], v145 offset:1024
	ds_read_b128 v[194:197], v145 offset:2048
	ds_read_b128 v[198:201], v145 offset:3072
	s_add_u32 s26, s24, 0xfffc0080
	s_addc_u32 s27, s25, -1
	s_cmp_eq_u32 s50, 12
	s_cselect_b32 s29, s1, s27
	s_cselect_b32 s28, s11, s26
	s_cselect_b32 s27, s17, s49
	s_cselect_b32 s26, s19, s48
	v_lshl_add_u64 v[150:151], s[24:25], 0, v[128:129]
	s_add_i32 m0, s33, 0xc000
	ds_read_b128 v[202:205], v146
	ds_read_b128 v[206:209], v146 offset:1024
	ds_read_b128 v[210:213], v146 offset:2048
	ds_read_b128 v[214:217], v146 offset:3072
	ds_read_b128 v[218:221], v146 offset:4096
	ds_read_b128 v[222:225], v146 offset:5120
	ds_read_b128 v[226:229], v146 offset:6144
	ds_read_b128 v[236:239], v146 offset:7168
	global_load_lds_dwordx4 v[150:151], off
	v_lshl_add_u64 v[150:151], s[24:25], 0, v[130:131]
	s_add_i32 m0, s33, 0xe000
	s_nop 0
	global_load_lds_dwordx4 v[150:151], off
	s_waitcnt vmcnt(8)
	s_waitcnt lgkmcnt(0)
	s_setprio 1
	s_barrier
	v_mfma_f32_16x16x32_bf16 v[124:127], v[136:139], v[202:205], 0
	v_mfma_f32_16x16x32_bf16 v[116:119], v[178:181], v[202:205], 0
	v_mfma_f32_16x16x32_bf16 v[108:111], v[136:139], v[210:213], 0
	v_mfma_f32_16x16x32_bf16 v[100:103], v[178:181], v[210:213], 0
	v_mfma_f32_16x16x32_bf16 v[92:95], v[136:139], v[218:221], 0
	v_mfma_f32_16x16x32_bf16 v[84:87], v[178:181], v[218:221], 0
	v_mfma_f32_16x16x32_bf16 v[76:79], v[136:139], v[226:229], 0
	v_mfma_f32_16x16x32_bf16 v[68:71], v[178:181], v[226:229], 0
	v_mfma_f32_16x16x32_bf16 v[124:127], v[174:177], v[206:209], v[124:127]
	v_mfma_f32_16x16x32_bf16 v[116:119], v[182:185], v[206:209], v[116:119]
	v_mfma_f32_16x16x32_bf16 v[108:111], v[174:177], v[214:217], v[108:111]
	v_mfma_f32_16x16x32_bf16 v[100:103], v[182:185], v[214:217], v[100:103]
	v_mfma_f32_16x16x32_bf16 v[92:95], v[174:177], v[222:225], v[92:95]
	v_mfma_f32_16x16x32_bf16 v[84:87], v[182:185], v[222:225], v[84:87]
	v_mfma_f32_16x16x32_bf16 v[76:79], v[174:177], v[236:239], v[76:79]
	v_mfma_f32_16x16x32_bf16 v[68:71], v[182:185], v[236:239], v[68:71]
	s_setprio 0
	s_setprio 1
	v_mfma_f32_16x16x32_bf16 v[120:123], v[186:189], v[202:205], 0
	v_mfma_f32_16x16x32_bf16 v[112:115], v[194:197], v[202:205], 0
	v_mfma_f32_16x16x32_bf16 v[104:107], v[186:189], v[210:213], 0
	v_mfma_f32_16x16x32_bf16 v[96:99], v[194:197], v[210:213], 0
	v_mfma_f32_16x16x32_bf16 v[88:91], v[186:189], v[218:221], 0
	v_mfma_f32_16x16x32_bf16 v[80:83], v[194:197], v[218:221], 0
	v_mfma_f32_16x16x32_bf16 v[72:75], v[186:189], v[226:229], 0
	v_mfma_f32_16x16x32_bf16 v[64:67], v[194:197], v[226:229], 0
	v_mfma_f32_16x16x32_bf16 v[120:123], v[190:193], v[206:209], v[120:123]
	v_mfma_f32_16x16x32_bf16 v[112:115], v[198:201], v[206:209], v[112:115]
	v_mfma_f32_16x16x32_bf16 v[104:107], v[190:193], v[214:217], v[104:107]
	v_mfma_f32_16x16x32_bf16 v[96:99], v[198:201], v[214:217], v[96:99]
	v_mfma_f32_16x16x32_bf16 v[88:91], v[190:193], v[222:225], v[88:91]
	v_mfma_f32_16x16x32_bf16 v[80:83], v[198:201], v[222:225], v[80:83]
	v_mfma_f32_16x16x32_bf16 v[72:75], v[190:193], v[236:239], v[72:75]
	v_mfma_f32_16x16x32_bf16 v[64:67], v[198:201], v[236:239], v[64:67]
	s_barrier
	s_setprio 0
	s_add_i32 s51, s44, s3
	v_lshl_add_u64 v[150:151], s[26:27], 0, v[158:159]
	s_mov_b32 m0, s51
	ds_read_b128 v[202:205], v146 offset:16384
	ds_read_b128 v[206:209], v146 offset:17408
	ds_read_b128 v[210:213], v146 offset:18432
	ds_read_b128 v[214:217], v146 offset:19456
	ds_read_b128 v[218:221], v146 offset:20480
	ds_read_b128 v[222:225], v146 offset:21504
	ds_read_b128 v[226:229], v146 offset:22528
	ds_read_b128 v[236:239], v146 offset:23552
	global_load_lds_dwordx4 v[150:151], off
	s_add_i32 m0, s51, 0x2000
	s_add_u32 s52, s26, 0x40000
	v_lshl_add_u64 v[246:247], s[26:27], 0, v[162:163]
	s_addc_u32 s53, s27, 0
	s_add_i32 s51, s45, s3
	global_load_lds_dwordx4 v[246:247], off
	v_lshl_add_u64 v[248:249], s[52:53], 0, v[158:159]
	s_mov_b32 m0, s51
	v_lshl_add_u64 v[250:251], s[28:29], 0, v[160:161]
	global_load_lds_dwordx4 v[248:249], off
	v_lshl_add_u64 v[248:249], s[52:53], 0, v[162:163]
	s_add_i32 m0, s51, 0x2000
	s_nop 0
	global_load_lds_dwordx4 v[248:249], off
	v_lshl_add_u64 v[248:249], s[28:29], 0, v[156:157]
	s_mov_b32 m0, s33
	s_nop 0
	global_load_lds_dwordx4 v[248:249], off
	s_mov_b32 m0, s34
	s_nop 0
	global_load_lds_dwordx4 v[250:251], off
	s_waitcnt vmcnt(8)
	s_waitcnt lgkmcnt(0)
	s_setprio 1
	s_barrier
; #define PG8_STAGE(bufoff, gbase, voff) do { _Pragma("unroll") for (int _i = 0; _i < 2; ++_i) \
;         __builtin_amdgcn_global_load_lds((const unsigned*)((const char*)(gbase) + (voff)[_i]), (PG8_LAS unsigned*)(lds + (bufoff) + ldsw + _i * 8192), 16, 0, 0); } while (0)
; #define PG8_LDA(dst, b, h) do { _Pragma("unroll") for (int m = 0; m < 4; ++m) _Pragma("unroll") for (int k = 0; k < 2; ++k) dst[m][k] = *(const PG8_LAS bf16x8*)(lds + PG8_SA(b, h) + aoff + m * 2048 + k * 1024); } while (0)
; #define PG8_LDB(dst, b, h) do { _Pragma("unroll") for (int n = 0; n < 2; ++n) _Pragma("unroll") for (int k = 0; k < 2; ++k) dst[n][k] = *(const PG8_LAS bf16x8*)(lds + PG8_SB(b, h) + boff + n * 2048 + k * 1024); } while (0)
; #define PG8_MMA(ai, bj, At, Bt) do { __builtin_amdgcn_s_setprio(1); _Pragma("unroll") for (int m = 0; m < 4; ++m) _Pragma("unroll") for (int n = 0; n < 2; ++n) _Pragma("unroll") for (int k = 0; k < 2; ++k) \
;         acc[ai][bj][m][n] = __builtin_amdgcn_mfma_f32_16x16x32_bf16(Bt[n][k], At[m][k], acc[ai][bj][m][n], 0, 0, 0); __builtin_amdgcn_s_setprio(0); } while (0)
; #define PG8_WAIT_V(n) asm volatile("s_waitcnt vmcnt(" #n ")" ::: "memory")
; #define PG8_WAIT_L(n) asm volatile("s_waitcnt lgkmcnt(" #n ")" ::: "memory")
; #define PG8_BAR __builtin_amdgcn_s_barrier()
; #define PG8_SCHED __builtin_amdgcn_sched_barrier(0)
; template <class Epi, class Sched, bool ALIGN_EPI = false, bool SP2 = false>
; __device__ __forceinline__ void gemm_phase(PG8_LAS unsigned char* lds, const Gemm g, const Sched& S, const Epi& E) {
;     ...
;             PG8_WAIT_V(8); PG8_WAIT_L(0); PG8_BAR; PG8_MMA(1, 0, At, B0); PG8_MMA(1, 1, At, B1); PG8_BAR; PG8_SCHED;
;             PG8_LDB(B0, 1, 0); PG8_LDB(B1, 1, 1); PG8_SCHED; PG8_LDA(At, 1, 0); PG8_STAGE(PG8_SA(0, 1), a2 + hstep, voffA);
;             PG8_WAIT_V(8); PG8_WAIT_L(0); PG8_BAR; PG8_MMA(0, 0, At, B0); PG8_MMA(0, 1, At, B1); PG8_BAR; PG8_SCHED;
	v_mfma_f32_16x16x32_bf16 v[60:63], v[136:139], v[202:205], 0
	v_mfma_f32_16x16x32_bf16 v[52:55], v[178:181], v[202:205], 0
	v_mfma_f32_16x16x32_bf16 v[44:47], v[136:139], v[210:213], 0
	v_mfma_f32_16x16x32_bf16 v[36:39], v[178:181], v[210:213], 0
	v_mfma_f32_16x16x32_bf16 v[28:31], v[136:139], v[218:221], 0
	v_mfma_f32_16x16x32_bf16 v[20:23], v[178:181], v[218:221], 0
	v_mfma_f32_16x16x32_bf16 v[12:15], v[136:139], v[226:229], 0
	v_mfma_f32_16x16x32_bf16 v[4:7], v[178:181], v[226:229], 0
	v_mfma_f32_16x16x32_bf16 v[60:63], v[174:177], v[206:209], v[60:63]
	v_mfma_f32_16x16x32_bf16 v[52:55], v[182:185], v[206:209], v[52:55]
	v_mfma_f32_16x16x32_bf16 v[44:47], v[174:177], v[214:217], v[44:47]
	v_mfma_f32_16x16x32_bf16 v[36:39], v[182:185], v[214:217], v[36:39]
	v_mfma_f32_16x16x32_bf16 v[28:31], v[174:177], v[222:225], v[28:31]
	v_mfma_f32_16x16x32_bf16 v[20:23], v[182:185], v[222:225], v[20:23]
	v_mfma_f32_16x16x32_bf16 v[12:15], v[174:177], v[236:239], v[12:15]
	v_mfma_f32_16x16x32_bf16 v[4:7], v[182:185], v[236:239], v[4:7]
	s_setprio 0
	s_setprio 1
	v_mfma_f32_16x16x32_bf16 v[56:59], v[186:189], v[202:205], 0
	v_mfma_f32_16x16x32_bf16 v[48:51], v[194:197], v[202:205], 0
	v_mfma_f32_16x16x32_bf16 v[40:43], v[186:189], v[210:213], 0
	v_mfma_f32_16x16x32_bf16 v[32:35], v[194:197], v[210:213], 0
	v_mfma_f32_16x16x32_bf16 v[24:27], v[186:189], v[218:221], 0
	v_mfma_f32_16x16x32_bf16 v[16:19], v[194:197], v[218:221], 0
	v_mfma_f32_16x16x32_bf16 v[8:11], v[186:189], v[226:229], 0
	v_mfma_f32_16x16x32_bf16 v[0:3], v[194:197], v[226:229], 0
	v_mfma_f32_16x16x32_bf16 v[56:59], v[190:193], v[206:209], v[56:59]
	v_mfma_f32_16x16x32_bf16 v[48:51], v[198:201], v[206:209], v[48:51]
	v_mfma_f32_16x16x32_bf16 v[40:43], v[190:193], v[214:217], v[40:43]
	v_mfma_f32_16x16x32_bf16 v[32:35], v[198:201], v[214:217], v[32:35]
	v_mfma_f32_16x16x32_bf16 v[24:27], v[190:193], v[222:225], v[24:27]
	v_mfma_f32_16x16x32_bf16 v[16:19], v[198:201], v[222:225], v[16:19]
	v_mfma_f32_16x16x32_bf16 v[8:11], v[190:193], v[236:239], v[8:11]
	v_mfma_f32_16x16x32_bf16 v[0:3], v[198:201], v[236:239], v[0:3]
	s_barrier
	s_setprio 0
	s_add_i32 s51, 0, 0x18000
	v_add_u32_e32 v149, s51, v141
	s_add_i32 s52, 0, 0x1c000
	ds_read_b128 v[136:139], v149
	ds_read_b128 v[174:177], v149 offset:1024
	ds_read_b128 v[178:181], v149 offset:2048
	ds_read_b128 v[182:185], v149 offset:3072
	v_add_u32_e32 v149, s52, v141
	ds_read_b128 v[186:189], v149
	ds_read_b128 v[190:193], v149 offset:1024
	ds_read_b128 v[194:197], v149 offset:2048
	ds_read_b128 v[198:201], v149 offset:3072
	s_add_u32 s28, s28, 0x40000
	s_addc_u32 s29, s29, 0
	s_mov_b32 m0, s35
	v_lshl_add_u64 v[252:253], s[28:29], 0, v[156:157]
	ds_read_b128 v[202:205], v146 offset:32768
	ds_read_b128 v[206:209], v146 offset:33792
	ds_read_b128 v[210:213], v146 offset:34816
	ds_read_b128 v[214:217], v146 offset:35840
	ds_read_b128 v[218:221], v146 offset:36864
	ds_read_b128 v[222:225], v146 offset:37888
	ds_read_b128 v[226:229], v146 offset:38912
	ds_read_b128 v[236:239], v146 offset:39936
	global_load_lds_dwordx4 v[252:253], off
	v_lshl_add_u64 v[252:253], s[28:29], 0, v[160:161]
	s_mov_b32 m0, s36
	s_nop 0
	global_load_lds_dwordx4 v[252:253], off
	s_waitcnt vmcnt(8)
	s_waitcnt lgkmcnt(0)
	s_setprio 1
	s_barrier
	v_mfma_f32_16x16x32_bf16 v[124:127], v[136:139], v[202:205], v[124:127]
	v_mfma_f32_16x16x32_bf16 v[116:119], v[178:181], v[202:205], v[116:119]
	v_mfma_f32_16x16x32_bf16 v[108:111], v[136:139], v[210:213], v[108:111]
	v_mfma_f32_16x16x32_bf16 v[100:103], v[178:181], v[210:213], v[100:103]
	v_mfma_f32_16x16x32_bf16 v[92:95], v[136:139], v[218:221], v[92:95]
	v_mfma_f32_16x16x32_bf16 v[84:87], v[178:181], v[218:221], v[84:87]
	v_mfma_f32_16x16x32_bf16 v[76:79], v[136:139], v[226:229], v[76:79]
	v_mfma_f32_16x16x32_bf16 v[68:71], v[178:181], v[226:229], v[68:71]
	v_mfma_f32_16x16x32_bf16 v[124:127], v[174:177], v[206:209], v[124:127]
	v_mfma_f32_16x16x32_bf16 v[116:119], v[182:185], v[206:209], v[116:119]
	v_mfma_f32_16x16x32_bf16 v[108:111], v[174:177], v[214:217], v[108:111]
	v_mfma_f32_16x16x32_bf16 v[100:103], v[182:185], v[214:217], v[100:103]
	v_mfma_f32_16x16x32_bf16 v[92:95], v[174:177], v[222:225], v[92:95]
	v_mfma_f32_16x16x32_bf16 v[84:87], v[182:185], v[222:225], v[84:87]
	v_mfma_f32_16x16x32_bf16 v[76:79], v[174:177], v[236:239], v[76:79]
	v_mfma_f32_16x16x32_bf16 v[68:71], v[182:185], v[236:239], v[68:71]
	s_setprio 0
	s_setprio 1
	v_mfma_f32_16x16x32_bf16 v[120:123], v[186:189], v[202:205], v[120:123]
	v_mfma_f32_16x16x32_bf16 v[112:115], v[194:197], v[202:205], v[112:115]
	v_mfma_f32_16x16x32_bf16 v[104:107], v[186:189], v[210:213], v[104:107]
	v_mfma_f32_16x16x32_bf16 v[96:99], v[194:197], v[210:213], v[96:99]
	v_mfma_f32_16x16x32_bf16 v[88:91], v[186:189], v[218:221], v[88:91]
	v_mfma_f32_16x16x32_bf16 v[80:83], v[194:197], v[218:221], v[80:83]
	v_mfma_f32_16x16x32_bf16 v[72:75], v[186:189], v[226:229], v[72:75]
	v_mfma_f32_16x16x32_bf16 v[64:67], v[194:197], v[226:229], v[64:67]
	v_mfma_f32_16x16x32_bf16 v[120:123], v[190:193], v[206:209], v[120:123]
	v_mfma_f32_16x16x32_bf16 v[112:115], v[198:201], v[206:209], v[112:115]
	v_mfma_f32_16x16x32_bf16 v[104:107], v[190:193], v[214:217], v[104:107]
	v_mfma_f32_16x16x32_bf16 v[96:99], v[198:201], v[214:217], v[96:99]
	v_mfma_f32_16x16x32_bf16 v[88:91], v[190:193], v[222:225], v[88:91]
	v_mfma_f32_16x16x32_bf16 v[80:83], v[198:201], v[222:225], v[80:83]
	v_mfma_f32_16x16x32_bf16 v[72:75], v[190:193], v[236:239], v[72:75]
	v_mfma_f32_16x16x32_bf16 v[64:67], v[198:201], v[236:239], v[64:67]
	s_barrier
; #define PG8_STAGE(bufoff, gbase, voff) do { _Pragma("unroll") for (int _i = 0; _i < 2; ++_i) \
;         __builtin_amdgcn_global_load_lds((const unsigned*)((const char*)(gbase) + (voff)[_i]), (PG8_LAS unsigned*)(lds + (bufoff) + ldsw + _i * 8192), 16, 0, 0); } while (0)
; #define PG8_LDA(dst, b, h) do { _Pragma("unroll") for (int m = 0; m < 4; ++m) _Pragma("unroll") for (int k = 0; k < 2; ++k) dst[m][k] = *(const PG8_LAS bf16x8*)(lds + PG8_SA(b, h) + aoff + m * 2048 + k * 1024); } while (0)
; #define PG8_MMA(ai, bj, At, Bt) do { __builtin_amdgcn_s_setprio(1); _Pragma("unroll") for (int m = 0; m < 4; ++m) _Pragma("unroll") for (int n = 0; n < 2; ++n) _Pragma("unroll") for (int k = 0; k < 2; ++k) \
;         acc[ai][bj][m][n] = __builtin_amdgcn_mfma_f32_16x16x32_bf16(Bt[n][k], At[m][k], acc[ai][bj][m][n], 0, 0, 0); __builtin_amdgcn_s_setprio(0); } while (0)
; #define PG8_WAIT_V(n) asm volatile("s_waitcnt vmcnt(" #n ")" ::: "memory")
; #define PG8_WAIT_L(n) asm volatile("s_waitcnt lgkmcnt(" #n ")" ::: "memory")
; #define PG8_BAR __builtin_amdgcn_s_barrier()
; #define PG8_SCHED __builtin_amdgcn_sched_barrier(0)
; template <class Epi, class Sched, bool ALIGN_EPI = false, bool SP2 = false>
; __device__ __forceinline__ void gemm_phase(PG8_LAS unsigned char* lds, const Gemm g, const Sched& S, const Epi& E) {
;     ...
;         for (int t = 0; t < nt; t += 2) {
;             const bool last = (t == nt - 2);
;             const char* a1 = cA + (size_t)(t + 1) * kstep;
;             const char* a2 = last ? nA : cA + (size_t)(t + 2) * kstep; const char* b2 = last ? nB : cB + (size_t)(t + 2) * kstep;
;             const char* a3 = a2 + kstep; const char* b3 = b2 + kstep;
;     ...
;             PG8_LDA(At, 1, 1); PG8_STAGE(PG8_SB(1, 0), b3, voffB); PG8_STAGE(PG8_SB(1, 1), b3 + hstep, voffB); PG8_STAGE(PG8_SA(1, 0), a3, voffA);
;             PG8_WAIT_V(8); PG8_WAIT_L(0); PG8_BAR; PG8_MMA(1, 0, At, B0); PG8_MMA(1, 1, At, B1); PG8_BAR; PG8_SCHED;
	s_setprio 0
	s_add_i32 s28, s51, s3
	v_lshl_add_u64 v[150:151], v[150:151], 0, s[6:7]
	s_mov_b32 m0, s28
	ds_read_b128 v[202:205], v146 offset:49152
	ds_read_b128 v[206:209], v146 offset:50176
	ds_read_b128 v[210:213], v146 offset:51200
	ds_read_b128 v[214:217], v146 offset:52224
	ds_read_b128 v[218:221], v146 offset:53248
	ds_read_b128 v[222:225], v146 offset:54272
	ds_read_b128 v[226:229], v146 offset:55296
	ds_read_b128 v[236:239], v146 offset:56320
	global_load_lds_dwordx4 v[150:151], off
	s_add_i32 m0, s28, 0x2000
	s_add_u32 s26, s26, 0x40080
	v_lshl_add_u64 v[150:151], v[246:247], 0, s[6:7]
	s_addc_u32 s27, s27, 0
	s_add_i32 s28, s52, s3
	global_load_lds_dwordx4 v[150:151], off
	v_lshl_add_u64 v[150:151], s[26:27], 0, v[158:159]
	s_mov_b32 m0, s28
	s_nop 0
	global_load_lds_dwordx4 v[150:151], off
	v_lshl_add_u64 v[150:151], s[26:27], 0, v[162:163]
	s_add_i32 m0, s28, 0x2000
	s_nop 0
	global_load_lds_dwordx4 v[150:151], off
	v_lshl_add_u64 v[150:151], v[248:249], 0, s[6:7]
	s_mov_b32 m0, s38
	s_nop 0
	global_load_lds_dwordx4 v[150:151], off
	v_lshl_add_u64 v[150:151], v[250:251], 0, s[6:7]
	s_mov_b32 m0, s39
	s_nop 0
	global_load_lds_dwordx4 v[150:151], off
	s_waitcnt vmcnt(8)
	s_waitcnt lgkmcnt(0)
	s_setprio 1
	s_barrier
	v_mfma_f32_16x16x32_bf16 v[60:63], v[136:139], v[202:205], v[60:63]
	v_mfma_f32_16x16x32_bf16 v[52:55], v[178:181], v[202:205], v[52:55]
	v_mfma_f32_16x16x32_bf16 v[44:47], v[136:139], v[210:213], v[44:47]
	v_mfma_f32_16x16x32_bf16 v[36:39], v[178:181], v[210:213], v[36:39]
	v_mfma_f32_16x16x32_bf16 v[28:31], v[136:139], v[218:221], v[28:31]
	v_mfma_f32_16x16x32_bf16 v[20:23], v[178:181], v[218:221], v[20:23]
	v_mfma_f32_16x16x32_bf16 v[12:15], v[136:139], v[226:229], v[12:15]
	v_mfma_f32_16x16x32_bf16 v[4:7], v[178:181], v[226:229], v[4:7]
	v_mfma_f32_16x16x32_bf16 v[60:63], v[174:177], v[206:209], v[60:63]
	v_mfma_f32_16x16x32_bf16 v[52:55], v[182:185], v[206:209], v[52:55]
	v_mfma_f32_16x16x32_bf16 v[44:47], v[174:177], v[214:217], v[44:47]
	v_mfma_f32_16x16x32_bf16 v[36:39], v[182:185], v[214:217], v[36:39]
	v_mfma_f32_16x16x32_bf16 v[28:31], v[174:177], v[222:225], v[28:31]
	v_mfma_f32_16x16x32_bf16 v[20:23], v[182:185], v[222:225], v[20:23]
	v_mfma_f32_16x16x32_bf16 v[12:15], v[174:177], v[236:239], v[12:15]
	v_mfma_f32_16x16x32_bf16 v[4:7], v[182:185], v[236:239], v[4:7]
	s_setprio 0
	s_setprio 1
	v_mfma_f32_16x16x32_bf16 v[56:59], v[186:189], v[202:205], v[56:59]
	v_mfma_f32_16x16x32_bf16 v[48:51], v[194:197], v[202:205], v[48:51]
	v_mfma_f32_16x16x32_bf16 v[40:43], v[186:189], v[210:213], v[40:43]
	v_mfma_f32_16x16x32_bf16 v[32:35], v[194:197], v[210:213], v[32:35]
	v_mfma_f32_16x16x32_bf16 v[24:27], v[186:189], v[218:221], v[24:27]
	v_mfma_f32_16x16x32_bf16 v[16:19], v[194:197], v[218:221], v[16:19]
	v_mfma_f32_16x16x32_bf16 v[8:11], v[186:189], v[226:229], v[8:11]
	v_mfma_f32_16x16x32_bf16 v[0:3], v[194:197], v[226:229], v[0:3]
	v_mfma_f32_16x16x32_bf16 v[56:59], v[190:193], v[206:209], v[56:59]
	v_mfma_f32_16x16x32_bf16 v[48:51], v[198:201], v[206:209], v[48:51]
	v_mfma_f32_16x16x32_bf16 v[40:43], v[190:193], v[214:217], v[40:43]
	v_mfma_f32_16x16x32_bf16 v[32:35], v[198:201], v[214:217], v[32:35]
	v_mfma_f32_16x16x32_bf16 v[24:27], v[190:193], v[222:225], v[24:27]
	v_mfma_f32_16x16x32_bf16 v[16:19], v[198:201], v[222:225], v[16:19]
	v_mfma_f32_16x16x32_bf16 v[8:11], v[190:193], v[236:239], v[8:11]
	v_mfma_f32_16x16x32_bf16 v[0:3], v[198:201], v[236:239], v[0:3]
	s_barrier
	s_setprio 0
	s_add_i32 s50, s50, 2
	s_add_u32 s24, s24, 0x100
	s_addc_u32 s25, s25, 0
	s_add_u32 s48, s48, 0x100
	s_addc_u32 s49, s49, 0
	s_cmp_gt_u32 s50, 13
	s_cbranch_scc1 .Lpeel_done_g4

; #define PG8_STAGE(bufoff, gbase, voff) do { _Pragma("unroll") for (int _i = 0; _i < 2; ++_i) \
;         __builtin_amdgcn_global_load_lds((const unsigned*)((const char*)(gbase) + (voff)[_i]), (PG8_LAS unsigned*)(lds + (bufoff) + ldsw + _i * 8192), 16, 0, 0); } while (0)
; #define PG8_LDA(dst, b, h) do { _Pragma("unroll") for (int m = 0; m < 4; ++m) _Pragma("unroll") for (int k = 0; k < 2; ++k) dst[m][k] = *(const PG8_LAS bf16x8*)(lds + PG8_SA(b, h) + aoff + m * 2048 + k * 1024); } while (0)
; #define PG8_LDB(dst, b, h) do { _Pragma("unroll") for (int n = 0; n < 2; ++n) _Pragma("unroll") for (int k = 0; k < 2; ++k) dst[n][k] = *(const PG8_LAS bf16x8*)(lds + PG8_SB(b, h) + boff + n * 2048 + k * 1024); } while (0)
; #define PG8_WAIT_V(n) asm volatile("s_waitcnt vmcnt(" #n ")" ::: "memory")
; #define PG8_WAIT_L(n) asm volatile("s_waitcnt lgkmcnt(" #n ")" ::: "memory")
; #define PG8_BAR __builtin_amdgcn_s_barrier()
; #define PG8_SCHED __builtin_amdgcn_sched_barrier(0)
; template <class Epi, class Sched, bool ALIGN_EPI = false, bool SP2 = false>
; __device__ __forceinline__ void gemm_phase(PG8_LAS unsigned char* lds, const Gemm g, const Sched& S, const Epi& E) {
;     ...
;             const char* a1 = cA + (size_t)(t + 1) * kstep;
;             const char* a2 = last ? nA : cA + (size_t)(t + 2) * kstep; const char* b2 = last ? nB : cB + (size_t)(t + 2) * kstep;
;             const char* a3 = a2 + kstep; const char* b3 = b2 + kstep;
;             if (last && has_next) S.a_ready(nxt);
;             if constexpr (SP2) {
;             PG8_LDB(B0, 0, 0); PG8_LDB(B1, 0, 1); PG8_SCHED; PG8_LDA(At, 0, 0); PG8_STAGE(PG8_SA(1, 1), a1 + hstep, voffA);
;             PG8_WAIT_V(8); PG8_WAIT_L(0); PG8_BAR; PG8_MMA(0, 0, At, B0); PG8_MMA(0, 1, At, B1); PG8_BAR; PG8_SCHED;
;             PG8_LDA(At, 0, 1); PG8_STAGE(PG8_SB(0, 0), b2, voffB); PG8_STAGE(PG8_SB(0, 1), b2 + hstep, voffB); PG8_STAGE(PG8_SA(0, 0), a2, voffA);
;             PG8_WAIT_V(8); PG8_WAIT_L(0); PG8_BAR; PG8_MMA(1, 0, At, B0); PG8_MMA(1, 1, At, B1); PG8_BAR; PG8_SCHED;
;     ...
; #pragma unroll
;         for (int a = 0; a < 2; ++a)
; #pragma unroll
;             for (int b = 0; b < 2; ++b)
; #pragma unroll
;                 for (int m = 0; m < 4; ++m)
; #pragma unroll
;                     for (int n = 0; n < 2; ++n) acc[a][b][m][n] = (f32x4){0.f, 0.f, 0.f, 0.f};
.LBB0_1441:
	s_add_u32 s6, s26, 0xb0080
	s_addc_u32 s7, s27, 0
	s_add_u32 s48, s10, 0x100
	s_addc_u32 s49, s11, 0
	s_mov_b32 s50, -2
	ds_read_b128 v[128:131], v213
	ds_read_b128 v[132:135], v213 offset:1024
	ds_read_b128 v[136:139], v213 offset:2048
	ds_read_b128 v[140:143], v213 offset:3072
	ds_read_b128 v[144:147], v214
	ds_read_b128 v[148:151], v214 offset:1024
	ds_read_b128 v[172:175], v214 offset:2048
	ds_read_b128 v[176:179], v214 offset:3072
	s_add_u32 s10, s6, 0xfff50080
	s_addc_u32 s11, s7, -1
	s_cmp_eq_u32 s50, 40
	s_cselect_b32 s27, s23, s11
	s_cselect_b32 s26, s22, s10
	s_cselect_b32 s11, s25, s49
	s_cselect_b32 s10, s24, s48
	v_lshl_add_u64 v[162:163], s[6:7], 0, v[154:155]
	s_add_i32 m0, s29, 0xc000
	ds_read_b128 v[180:183], v215
	ds_read_b128 v[184:187], v215 offset:1024
	ds_read_b128 v[188:191], v215 offset:2048
	ds_read_b128 v[192:195], v215 offset:3072
	ds_read_b128 v[196:199], v215 offset:4096
	ds_read_b128 v[200:203], v215 offset:5120
	ds_read_b128 v[204:207], v215 offset:6144
	ds_read_b128 v[220:223], v215 offset:7168
	global_load_lds_dwordx4 v[162:163], off
	v_lshl_add_u64 v[162:163], s[6:7], 0, v[156:157]
	s_add_i32 m0, s29, 0xe000
	s_nop 0
	global_load_lds_dwordx4 v[162:163], off
	s_waitcnt vmcnt(8)
	s_waitcnt lgkmcnt(0)
	s_setprio 1
	s_barrier
	v_mfma_f32_16x16x32_bf16 v[124:127], v[128:131], v[180:183], 0
	v_mfma_f32_16x16x32_bf16 v[120:123], v[136:139], v[180:183], 0
	v_mfma_f32_16x16x32_bf16 v[108:111], v[128:131], v[188:191], 0
	v_mfma_f32_16x16x32_bf16 v[104:107], v[136:139], v[188:191], 0
	v_mfma_f32_16x16x32_bf16 v[92:95], v[128:131], v[196:199], 0
	v_mfma_f32_16x16x32_bf16 v[88:91], v[136:139], v[196:199], 0
	v_mfma_f32_16x16x32_bf16 v[76:79], v[128:131], v[204:207], 0
	v_mfma_f32_16x16x32_bf16 v[72:75], v[136:139], v[204:207], 0
	v_mfma_f32_16x16x32_bf16 v[124:127], v[132:135], v[184:187], v[124:127]
	v_mfma_f32_16x16x32_bf16 v[120:123], v[140:143], v[184:187], v[120:123]
	v_mfma_f32_16x16x32_bf16 v[108:111], v[132:135], v[192:195], v[108:111]
	v_mfma_f32_16x16x32_bf16 v[104:107], v[140:143], v[192:195], v[104:107]
	v_mfma_f32_16x16x32_bf16 v[92:95], v[132:135], v[200:203], v[92:95]
	v_mfma_f32_16x16x32_bf16 v[88:91], v[140:143], v[200:203], v[88:91]
	v_mfma_f32_16x16x32_bf16 v[76:79], v[132:135], v[220:223], v[76:79]
	v_mfma_f32_16x16x32_bf16 v[72:75], v[140:143], v[220:223], v[72:75]
	s_setprio 0
	s_setprio 1
	v_mfma_f32_16x16x32_bf16 v[116:119], v[144:147], v[180:183], 0
	v_mfma_f32_16x16x32_bf16 v[112:115], v[172:175], v[180:183], 0
	v_mfma_f32_16x16x32_bf16 v[100:103], v[144:147], v[188:191], 0
	v_mfma_f32_16x16x32_bf16 v[96:99], v[172:175], v[188:191], 0
	v_mfma_f32_16x16x32_bf16 v[84:87], v[144:147], v[196:199], 0
	v_mfma_f32_16x16x32_bf16 v[80:83], v[172:175], v[196:199], 0
	v_mfma_f32_16x16x32_bf16 v[68:71], v[144:147], v[204:207], 0
	v_mfma_f32_16x16x32_bf16 v[64:67], v[172:175], v[204:207], 0
	v_mfma_f32_16x16x32_bf16 v[116:119], v[148:151], v[184:187], v[116:119]
	v_mfma_f32_16x16x32_bf16 v[112:115], v[176:179], v[184:187], v[112:115]
	v_mfma_f32_16x16x32_bf16 v[100:103], v[148:151], v[192:195], v[100:103]
	v_mfma_f32_16x16x32_bf16 v[96:99], v[176:179], v[192:195], v[96:99]
	v_mfma_f32_16x16x32_bf16 v[84:87], v[148:151], v[200:203], v[84:87]
	v_mfma_f32_16x16x32_bf16 v[80:83], v[176:179], v[200:203], v[80:83]
	v_mfma_f32_16x16x32_bf16 v[68:71], v[148:151], v[220:223], v[68:71]
	v_mfma_f32_16x16x32_bf16 v[64:67], v[176:179], v[220:223], v[64:67]
	s_barrier
	s_setprio 0
	s_add_i32 s51, s41, s28
	v_lshl_add_u64 v[162:163], s[10:11], 0, v[166:167]
	s_mov_b32 m0, s51
	ds_read_b128 v[180:183], v215 offset:16384
	ds_read_b128 v[184:187], v215 offset:17408
	ds_read_b128 v[188:191], v215 offset:18432
	ds_read_b128 v[192:195], v215 offset:19456
	ds_read_b128 v[196:199], v215 offset:20480
	ds_read_b128 v[200:203], v215 offset:21504
	ds_read_b128 v[204:207], v215 offset:22528
	ds_read_b128 v[220:223], v215 offset:23552
	global_load_lds_dwordx4 v[162:163], off
	s_add_i32 m0, s51, 0x2000
	s_add_u32 s52, s10, 0xb0000
	v_lshl_add_u64 v[208:209], s[10:11], 0, v[170:171]
	s_addc_u32 s53, s11, 0
	s_add_i32 s51, s42, s28
	global_load_lds_dwordx4 v[208:209], off
	v_lshl_add_u64 v[224:225], s[52:53], 0, v[166:167]
	s_mov_b32 m0, s51
	v_lshl_add_u64 v[226:227], s[26:27], 0, v[168:169]
	global_load_lds_dwordx4 v[224:225], off
	v_lshl_add_u64 v[224:225], s[52:53], 0, v[170:171]
	s_add_i32 m0, s51, 0x2000
	s_nop 0
	global_load_lds_dwordx4 v[224:225], off
	v_lshl_add_u64 v[224:225], s[26:27], 0, v[164:165]
	s_mov_b32 m0, s29
	s_nop 0
	global_load_lds_dwordx4 v[224:225], off
	s_mov_b32 m0, s30
	s_nop 0
	global_load_lds_dwordx4 v[226:227], off
	s_waitcnt vmcnt(8)
	s_waitcnt lgkmcnt(0)
	s_setprio 1
	s_barrier
; #define PG8_STAGE(bufoff, gbase, voff) do { _Pragma("unroll") for (int _i = 0; _i < 2; ++_i) \
;         __builtin_amdgcn_global_load_lds((const unsigned*)((const char*)(gbase) + (voff)[_i]), (PG8_LAS unsigned*)(lds + (bufoff) + ldsw + _i * 8192), 16, 0, 0); } while (0)
; #define PG8_LDA(dst, b, h) do { _Pragma("unroll") for (int m = 0; m < 4; ++m) _Pragma("unroll") for (int k = 0; k < 2; ++k) dst[m][k] = *(const PG8_LAS bf16x8*)(lds + PG8_SA(b, h) + aoff + m * 2048 + k * 1024); } while (0)
; #define PG8_LDB(dst, b, h) do { _Pragma("unroll") for (int n = 0; n < 2; ++n) _Pragma("unroll") for (int k = 0; k < 2; ++k) dst[n][k] = *(const PG8_LAS bf16x8*)(lds + PG8_SB(b, h) + boff + n * 2048 + k * 1024); } while (0)
; #define PG8_MMA(ai, bj, At, Bt) do { __builtin_amdgcn_s_setprio(1); _Pragma("unroll") for (int m = 0; m < 4; ++m) _Pragma("unroll") for (int n = 0; n < 2; ++n) _Pragma("unroll") for (int k = 0; k < 2; ++k) \
;         acc[ai][bj][m][n] = __builtin_amdgcn_mfma_f32_16x16x32_bf16(Bt[n][k], At[m][k], acc[ai][bj][m][n], 0, 0, 0); __builtin_amdgcn_s_setprio(0); } while (0)
; #define PG8_WAIT_V(n) asm volatile("s_waitcnt vmcnt(" #n ")" ::: "memory")
; #define PG8_WAIT_L(n) asm volatile("s_waitcnt lgkmcnt(" #n ")" ::: "memory")
; #define PG8_BAR __builtin_amdgcn_s_barrier()
; #define PG8_SCHED __builtin_amdgcn_sched_barrier(0)
; template <class Epi, class Sched, bool ALIGN_EPI = false, bool SP2 = false>
; __device__ __forceinline__ void gemm_phase(PG8_LAS unsigned char* lds, const Gemm g, const Sched& S, const Epi& E) {
;     ...
;             PG8_WAIT_V(8); PG8_WAIT_L(0); PG8_BAR; PG8_MMA(1, 0, At, B0); PG8_MMA(1, 1, At, B1); PG8_BAR; PG8_SCHED;
;             PG8_LDB(B0, 1, 0); PG8_LDB(B1, 1, 1); PG8_SCHED; PG8_LDA(At, 1, 0); PG8_STAGE(PG8_SA(0, 1), a2 + hstep, voffA);
;             PG8_WAIT_V(8); PG8_WAIT_L(0); PG8_BAR; PG8_MMA(0, 0, At, B0); PG8_MMA(0, 1, At, B1); PG8_BAR; PG8_SCHED;
	v_mfma_f32_16x16x32_bf16 v[60:63], v[128:131], v[180:183], 0
	v_mfma_f32_16x16x32_bf16 v[56:59], v[136:139], v[180:183], 0
	v_mfma_f32_16x16x32_bf16 v[44:47], v[128:131], v[188:191], 0
	v_mfma_f32_16x16x32_bf16 v[40:43], v[136:139], v[188:191], 0
	v_mfma_f32_16x16x32_bf16 v[28:31], v[128:131], v[196:199], 0
	v_mfma_f32_16x16x32_bf16 v[24:27], v[136:139], v[196:199], 0
	v_mfma_f32_16x16x32_bf16 v[12:15], v[128:131], v[204:207], 0
	v_mfma_f32_16x16x32_bf16 v[8:11], v[136:139], v[204:207], 0
	v_mfma_f32_16x16x32_bf16 v[60:63], v[132:135], v[184:187], v[60:63]
	v_mfma_f32_16x16x32_bf16 v[56:59], v[140:143], v[184:187], v[56:59]
	v_mfma_f32_16x16x32_bf16 v[44:47], v[132:135], v[192:195], v[44:47]
	v_mfma_f32_16x16x32_bf16 v[40:43], v[140:143], v[192:195], v[40:43]
	v_mfma_f32_16x16x32_bf16 v[28:31], v[132:135], v[200:203], v[28:31]
	v_mfma_f32_16x16x32_bf16 v[24:27], v[140:143], v[200:203], v[24:27]
	v_mfma_f32_16x16x32_bf16 v[12:15], v[132:135], v[220:223], v[12:15]
	v_mfma_f32_16x16x32_bf16 v[8:11], v[140:143], v[220:223], v[8:11]
	s_setprio 0
	s_setprio 1
	v_mfma_f32_16x16x32_bf16 v[52:55], v[144:147], v[180:183], 0
	v_mfma_f32_16x16x32_bf16 v[48:51], v[172:175], v[180:183], 0
	v_mfma_f32_16x16x32_bf16 v[36:39], v[144:147], v[188:191], 0
	v_mfma_f32_16x16x32_bf16 v[32:35], v[172:175], v[188:191], 0
	v_mfma_f32_16x16x32_bf16 v[20:23], v[144:147], v[196:199], 0
	v_mfma_f32_16x16x32_bf16 v[16:19], v[172:175], v[196:199], 0
	v_mfma_f32_16x16x32_bf16 v[4:7], v[144:147], v[204:207], 0
	v_mfma_f32_16x16x32_bf16 v[0:3], v[172:175], v[204:207], 0
	v_mfma_f32_16x16x32_bf16 v[52:55], v[148:151], v[184:187], v[52:55]
	v_mfma_f32_16x16x32_bf16 v[48:51], v[176:179], v[184:187], v[48:51]
	v_mfma_f32_16x16x32_bf16 v[36:39], v[148:151], v[192:195], v[36:39]
	v_mfma_f32_16x16x32_bf16 v[32:35], v[176:179], v[192:195], v[32:35]
	v_mfma_f32_16x16x32_bf16 v[20:23], v[148:151], v[200:203], v[20:23]
	v_mfma_f32_16x16x32_bf16 v[16:19], v[176:179], v[200:203], v[16:19]
	v_mfma_f32_16x16x32_bf16 v[4:7], v[148:151], v[220:223], v[4:7]
	v_mfma_f32_16x16x32_bf16 v[0:3], v[176:179], v[220:223], v[0:3]
	s_barrier
	s_setprio 0
	s_add_i32 s51, 0, 0x18000
	s_add_i32 s52, 0, 0x1c000
	v_add_u32_e32 v140, s51, v211
	v_add_u32_e32 v176, s52, v211
	ds_read_b128 v[128:131], v140
	ds_read_b128 v[132:135], v140 offset:1024
	ds_read_b128 v[136:139], v140 offset:2048
	ds_read_b128 v[140:143], v140 offset:3072
	ds_read_b128 v[144:147], v176
	ds_read_b128 v[148:151], v176 offset:1024
	ds_read_b128 v[172:175], v176 offset:2048
	ds_read_b128 v[176:179], v176 offset:3072
	s_add_u32 s26, s26, 0xb0000
	s_addc_u32 s27, s27, 0
	s_mov_b32 m0, s31
	v_lshl_add_u64 v[228:229], s[26:27], 0, v[164:165]
	ds_read_b128 v[180:183], v215 offset:32768
	ds_read_b128 v[184:187], v215 offset:33792
	ds_read_b128 v[188:191], v215 offset:34816
	ds_read_b128 v[192:195], v215 offset:35840
	ds_read_b128 v[196:199], v215 offset:36864
	ds_read_b128 v[200:203], v215 offset:37888
	ds_read_b128 v[204:207], v215 offset:38912
	ds_read_b128 v[220:223], v215 offset:39936
	global_load_lds_dwordx4 v[228:229], off
	v_lshl_add_u64 v[228:229], s[26:27], 0, v[168:169]
	s_mov_b32 m0, s33
	s_nop 0
	global_load_lds_dwordx4 v[228:229], off
	s_waitcnt vmcnt(8)
	s_waitcnt lgkmcnt(0)
	s_setprio 1
	s_barrier
	v_mfma_f32_16x16x32_bf16 v[124:127], v[128:131], v[180:183], v[124:127]
	v_mfma_f32_16x16x32_bf16 v[120:123], v[136:139], v[180:183], v[120:123]
	v_mfma_f32_16x16x32_bf16 v[108:111], v[128:131], v[188:191], v[108:111]
	v_mfma_f32_16x16x32_bf16 v[104:107], v[136:139], v[188:191], v[104:107]
	v_mfma_f32_16x16x32_bf16 v[92:95], v[128:131], v[196:199], v[92:95]
	v_mfma_f32_16x16x32_bf16 v[88:91], v[136:139], v[196:199], v[88:91]
	v_mfma_f32_16x16x32_bf16 v[76:79], v[128:131], v[204:207], v[76:79]
	v_mfma_f32_16x16x32_bf16 v[72:75], v[136:139], v[204:207], v[72:75]
	v_mfma_f32_16x16x32_bf16 v[124:127], v[132:135], v[184:187], v[124:127]
	v_mfma_f32_16x16x32_bf16 v[120:123], v[140:143], v[184:187], v[120:123]
	v_mfma_f32_16x16x32_bf16 v[108:111], v[132:135], v[192:195], v[108:111]
	v_mfma_f32_16x16x32_bf16 v[104:107], v[140:143], v[192:195], v[104:107]
	v_mfma_f32_16x16x32_bf16 v[92:95], v[132:135], v[200:203], v[92:95]
	v_mfma_f32_16x16x32_bf16 v[88:91], v[140:143], v[200:203], v[88:91]
	v_mfma_f32_16x16x32_bf16 v[76:79], v[132:135], v[220:223], v[76:79]
	v_mfma_f32_16x16x32_bf16 v[72:75], v[140:143], v[220:223], v[72:75]
	s_setprio 0
	s_setprio 1
	v_mfma_f32_16x16x32_bf16 v[116:119], v[144:147], v[180:183], v[116:119]
	v_mfma_f32_16x16x32_bf16 v[112:115], v[172:175], v[180:183], v[112:115]
	v_mfma_f32_16x16x32_bf16 v[100:103], v[144:147], v[188:191], v[100:103]
	v_mfma_f32_16x16x32_bf16 v[96:99], v[172:175], v[188:191], v[96:99]
	v_mfma_f32_16x16x32_bf16 v[84:87], v[144:147], v[196:199], v[84:87]
	v_mfma_f32_16x16x32_bf16 v[80:83], v[172:175], v[196:199], v[80:83]
	v_mfma_f32_16x16x32_bf16 v[68:71], v[144:147], v[204:207], v[68:71]
	v_mfma_f32_16x16x32_bf16 v[64:67], v[172:175], v[204:207], v[64:67]
	v_mfma_f32_16x16x32_bf16 v[116:119], v[148:151], v[184:187], v[116:119]
	v_mfma_f32_16x16x32_bf16 v[112:115], v[176:179], v[184:187], v[112:115]
	v_mfma_f32_16x16x32_bf16 v[100:103], v[148:151], v[192:195], v[100:103]
	v_mfma_f32_16x16x32_bf16 v[96:99], v[176:179], v[192:195], v[96:99]
	v_mfma_f32_16x16x32_bf16 v[84:87], v[148:151], v[200:203], v[84:87]
	v_mfma_f32_16x16x32_bf16 v[80:83], v[176:179], v[200:203], v[80:83]
	v_mfma_f32_16x16x32_bf16 v[68:71], v[148:151], v[220:223], v[68:71]
	v_mfma_f32_16x16x32_bf16 v[64:67], v[176:179], v[220:223], v[64:67]
	s_barrier
; #define PG8_STAGE(bufoff, gbase, voff) do { _Pragma("unroll") for (int _i = 0; _i < 2; ++_i) \
;         __builtin_amdgcn_global_load_lds((const unsigned*)((const char*)(gbase) + (voff)[_i]), (PG8_LAS unsigned*)(lds + (bufoff) + ldsw + _i * 8192), 16, 0, 0); } while (0)
; #define PG8_LDA(dst, b, h) do { _Pragma("unroll") for (int m = 0; m < 4; ++m) _Pragma("unroll") for (int k = 0; k < 2; ++k) dst[m][k] = *(const PG8_LAS bf16x8*)(lds + PG8_SA(b, h) + aoff + m * 2048 + k * 1024); } while (0)
; #define PG8_MMA(ai, bj, At, Bt) do { __builtin_amdgcn_s_setprio(1); _Pragma("unroll") for (int m = 0; m < 4; ++m) _Pragma("unroll") for (int n = 0; n < 2; ++n) _Pragma("unroll") for (int k = 0; k < 2; ++k) \
;         acc[ai][bj][m][n] = __builtin_amdgcn_mfma_f32_16x16x32_bf16(Bt[n][k], At[m][k], acc[ai][bj][m][n], 0, 0, 0); __builtin_amdgcn_s_setprio(0); } while (0)
; #define PG8_WAIT_V(n) asm volatile("s_waitcnt vmcnt(" #n ")" ::: "memory")
; #define PG8_WAIT_L(n) asm volatile("s_waitcnt lgkmcnt(" #n ")" ::: "memory")
; #define PG8_BAR __builtin_amdgcn_s_barrier()
; #define PG8_SCHED __builtin_amdgcn_sched_barrier(0)
; template <class Epi, class Sched, bool ALIGN_EPI = false, bool SP2 = false>
; __device__ __forceinline__ void gemm_phase(PG8_LAS unsigned char* lds, const Gemm g, const Sched& S, const Epi& E) {
;     ...
;         for (int t = 0; t < nt; t += 2) {
;             const bool last = (t == nt - 2);
;             const char* a1 = cA + (size_t)(t + 1) * kstep;
;             const char* a2 = last ? nA : cA + (size_t)(t + 2) * kstep; const char* b2 = last ? nB : cB + (size_t)(t + 2) * kstep;
;             const char* a3 = a2 + kstep; const char* b3 = b2 + kstep;
;     ...
;             PG8_LDA(At, 1, 1); PG8_STAGE(PG8_SB(1, 0), b3, voffB); PG8_STAGE(PG8_SB(1, 1), b3 + hstep, voffB); PG8_STAGE(PG8_SA(1, 0), a3, voffA);
;             PG8_WAIT_V(8); PG8_WAIT_L(0); PG8_BAR; PG8_MMA(1, 0, At, B0); PG8_MMA(1, 1, At, B1); PG8_BAR; PG8_SCHED;
	s_setprio 0
	s_add_i32 s26, s51, s28
	v_lshl_add_u64 v[162:163], v[162:163], 0, s[18:19]
	s_mov_b32 m0, s26
	ds_read_b128 v[180:183], v215 offset:49152
	ds_read_b128 v[184:187], v215 offset:50176
	ds_read_b128 v[188:191], v215 offset:51200
	ds_read_b128 v[192:195], v215 offset:52224
	ds_read_b128 v[196:199], v215 offset:53248
	ds_read_b128 v[200:203], v215 offset:54272
	ds_read_b128 v[204:207], v215 offset:55296
	ds_read_b128 v[220:223], v215 offset:56320
	global_load_lds_dwordx4 v[162:163], off
	s_add_i32 m0, s26, 0x2000
	s_add_u32 s10, s10, 0xb0080
	v_lshl_add_u64 v[162:163], v[208:209], 0, s[18:19]
	s_addc_u32 s11, s11, 0
	s_add_i32 s26, s52, s28
	global_load_lds_dwordx4 v[162:163], off
	v_lshl_add_u64 v[162:163], s[10:11], 0, v[166:167]
	s_mov_b32 m0, s26
	s_nop 0
	global_load_lds_dwordx4 v[162:163], off
	v_lshl_add_u64 v[162:163], s[10:11], 0, v[170:171]
	s_add_i32 m0, s26, 0x2000
	s_nop 0
	global_load_lds_dwordx4 v[162:163], off
	v_lshl_add_u64 v[162:163], v[224:225], 0, s[18:19]
	s_mov_b32 m0, s37
	s_nop 0
	global_load_lds_dwordx4 v[162:163], off
	v_lshl_add_u64 v[162:163], v[226:227], 0, s[18:19]
	s_mov_b32 m0, s38
	s_nop 0
	global_load_lds_dwordx4 v[162:163], off
	s_waitcnt vmcnt(8)
	s_waitcnt lgkmcnt(0)
	s_setprio 1
	s_barrier
	v_mfma_f32_16x16x32_bf16 v[60:63], v[128:131], v[180:183], v[60:63]
	v_mfma_f32_16x16x32_bf16 v[56:59], v[136:139], v[180:183], v[56:59]
	v_mfma_f32_16x16x32_bf16 v[44:47], v[128:131], v[188:191], v[44:47]
	v_mfma_f32_16x16x32_bf16 v[40:43], v[136:139], v[188:191], v[40:43]
	v_mfma_f32_16x16x32_bf16 v[28:31], v[128:131], v[196:199], v[28:31]
	v_mfma_f32_16x16x32_bf16 v[24:27], v[136:139], v[196:199], v[24:27]
	v_mfma_f32_16x16x32_bf16 v[12:15], v[128:131], v[204:207], v[12:15]
	v_mfma_f32_16x16x32_bf16 v[8:11], v[136:139], v[204:207], v[8:11]
	v_mfma_f32_16x16x32_bf16 v[60:63], v[132:135], v[184:187], v[60:63]
	v_mfma_f32_16x16x32_bf16 v[56:59], v[140:143], v[184:187], v[56:59]
	v_mfma_f32_16x16x32_bf16 v[44:47], v[132:135], v[192:195], v[44:47]
	v_mfma_f32_16x16x32_bf16 v[40:43], v[140:143], v[192:195], v[40:43]
	v_mfma_f32_16x16x32_bf16 v[28:31], v[132:135], v[200:203], v[28:31]
	v_mfma_f32_16x16x32_bf16 v[24:27], v[140:143], v[200:203], v[24:27]
	v_mfma_f32_16x16x32_bf16 v[12:15], v[132:135], v[220:223], v[12:15]
	v_mfma_f32_16x16x32_bf16 v[8:11], v[140:143], v[220:223], v[8:11]
	s_setprio 0
	s_setprio 1
	v_mfma_f32_16x16x32_bf16 v[52:55], v[144:147], v[180:183], v[52:55]
	v_mfma_f32_16x16x32_bf16 v[48:51], v[172:175], v[180:183], v[48:51]
	v_mfma_f32_16x16x32_bf16 v[36:39], v[144:147], v[188:191], v[36:39]
	v_mfma_f32_16x16x32_bf16 v[32:35], v[172:175], v[188:191], v[32:35]
	v_mfma_f32_16x16x32_bf16 v[20:23], v[144:147], v[196:199], v[20:23]
	v_mfma_f32_16x16x32_bf16 v[16:19], v[172:175], v[196:199], v[16:19]
	v_mfma_f32_16x16x32_bf16 v[4:7], v[144:147], v[204:207], v[4:7]
	v_mfma_f32_16x16x32_bf16 v[0:3], v[172:175], v[204:207], v[0:3]
	v_mfma_f32_16x16x32_bf16 v[52:55], v[148:151], v[184:187], v[52:55]
	v_mfma_f32_16x16x32_bf16 v[48:51], v[176:179], v[184:187], v[48:51]
	v_mfma_f32_16x16x32_bf16 v[36:39], v[148:151], v[192:195], v[36:39]
	v_mfma_f32_16x16x32_bf16 v[32:35], v[176:179], v[192:195], v[32:35]
	v_mfma_f32_16x16x32_bf16 v[20:23], v[148:151], v[200:203], v[20:23]
	v_mfma_f32_16x16x32_bf16 v[16:19], v[176:179], v[200:203], v[16:19]
	v_mfma_f32_16x16x32_bf16 v[4:7], v[148:151], v[220:223], v[4:7]
	v_mfma_f32_16x16x32_bf16 v[0:3], v[176:179], v[220:223], v[0:3]
	s_barrier
	s_setprio 0
	s_add_i32 s50, s50, 2
	s_add_u32 s6, s6, 0x100
	s_addc_u32 s7, s7, 0
	s_add_u32 s48, s48, 0x100
	s_addc_u32 s49, s49, 0
	s_cmp_gt_u32 s50, 41
	s_cbranch_scc1 .Lpeel_done_g5

; #define PG8_BAR __builtin_amdgcn_s_barrier()
; template <class Epi, class Sched, bool ALIGN_EPI = false, bool SP2 = false>
; __device__ __forceinline__ void gemm_phase(PG8_LAS unsigned char* lds, const Gemm g, const Sched& S, const Epi& E) {
;     ...
;         if constexpr (ALIGN_EPI) { if (wr == 0) PG8_BAR; }
.Lpeel_done_g5:
	s_and_b64 vcc, exec, s[20:21]
	s_cbranch_vccz .LBB0_1445
	s_barrier
